# k43 + POST rope table: 9 distinct LDS vectors read once per iteration into free VGPRs, 58 repeated ds_read_b128 removed by operand renaming
# speedup vs baseline: 1.0054x; 1.0054x over previous
; #define LAS __attribute__((address_space(3)))
; DI unsigned pk2(float lo, float hi) { f32x2 x = {lo, hi}; return __builtin_bit_cast(unsigned, __builtin_convertvector(x, bf16x2_t)); }
; DI float sum32(float v) { v += __shfl_xor(v, 16); return sum16(v); }
; DI f32x2 unpk(unsigned w) { f32x2 r = {bflo(w), bfhi(w)}; return r; }
; template <int HP> DI void rope2(f32x2& x, int hl, const LAS f32x2* cs) {
;   const float pa = __shfl_xor(x[0], HP), pb = __shfl_xor(x[1], HP);
;   if (hl < HP) { const f32x2 c0 = cs[2 * hl], c1 = cs[2 * hl + 1]; x[0] = x[0] * c0[0] - pa * c0[1]; x[1] = x[1] * c1[0] - pb * c1[1]; }
;   else if (hl < 2 * HP) { const f32x2 c0 = cs[2 * (hl - HP)], c1 = cs[2 * (hl - HP) + 1]; x[0] = x[0] * c0[0] + pa * c0[1]; x[1] = x[1] * c1[0] + pb * c1[1]; }
; DI void post_unit(const Params& p, int l, int unit, LAS unsigned char* lds) {
;     ...
;   for (int tp = 0; tp < 4; ++tp) {
;     constexpr int segcol[16] = {C_QA, C_QA + 128, C_KA, C_QI, C_QI + 128, C_QI + 256, C_QI + 384, C_KI, C_QB, C_QB + 128, C_KB, C_KB + 128, C_QC, C_QC + 128, C_KC, C_KC + 128};
;     unsigned raw2[2][16];
; #pragma unroll
;     for (int hf = 0; hf < 2; ++hf) { const u16* rowl = proj + (tok0 + w * 8 + 2 * tp + hf) * NP;
; #pragma unroll
;       for (int s = 0; s < 16; ++s) raw2[hf][s] = *(const unsigned*)(rowl + segcol[s] + 2 * lane); }
; #pragma unroll
;     for (int hf = 0; hf < 2; ++hf) {
;     const int t = w * 8 + 2 * tp + hf; u16* row = proj + (tok0 + t) * NP;
; #pragma unroll
;     for (int s = 0; s < 16; ++s) {
;       f32x2 x = unpk(raw2[hf][s]); u16* pp = row + segcol[s] + 2 * lane;
;       if (s < 2) {
;         const float rs = rsqrtf(sum32(x[0] * x[0] + x[1] * x[1]) * (1.0f / 64.0f) + EPS);
;         x[0] *= rs * qna[2 * hl]; x[1] *= rs * qna[2 * hl + 1]; rope2<4>(x, hl, cs16 + t * 8);
;         x *= LOG2E * 0.125f; *(unsigned*)pp = pk2(x[0], x[1]);
.LBB0_150:
	ds_read_b128 v[208:211], v35
	ds_read_b128 v[212:215], v35 offset:64
	ds_read_b128 v[216:219], v39
	ds_read_b128 v[220:223], v39 offset:256
	ds_read_b128 v[224:227], v40
	ds_read_b128 v[228:231], v40 offset:32
	ds_read_b128 v[232:235], v35 offset:128
	ds_read_b128 v[236:239], v39 offset:512
	ds_read_b128 v[240:243], v40 offset:64
	s_waitcnt lgkmcnt(0)
	v_lshl_add_u64 v[18:19], v[12:13], 0, v[0:1]
	v_add_co_u32_e32 v20, vcc, 0xa000000, v18
	s_mov_b32 s2, 0xa001000
	s_waitcnt lgkmcnt(0)
	v_addc_co_u32_e32 v21, vcc, 0, v19, vcc
	global_load_dword v49, v[20:21], off
	v_add_co_u32_e32 v22, vcc, s2, v18
	s_mov_b32 s2, 0xa003000
	s_nop 0
	v_addc_co_u32_e32 v23, vcc, 0, v19, vcc
	v_add_co_u32_e32 v42, vcc, s77, v18
	global_load_dword v59, v[20:21], off offset:512
	global_load_dword v70, v[20:21], off offset:768
	global_load_dword v69, v[20:21], off offset:1024
	global_load_dword v68, v[20:21], off offset:1280
	global_load_dword v67, v[20:21], off offset:1536
	global_load_dword v58, v[20:21], off offset:1792
	global_load_dword v71, v[20:21], off offset:256
	v_addc_co_u32_e32 v43, vcc, 0, v19, vcc
	global_load_dword v56, v[20:21], off offset:2432
	global_load_dword v66, v[20:21], off offset:2688
	global_load_dword v65, v[20:21], off offset:2944
	global_load_dword v64, v[20:21], off offset:3200
	global_load_dword v54, v[22:23], off offset:384
	global_load_dword v63, v[22:23], off offset:640
	global_load_dword v62, v[22:23], off offset:896
	global_load_dword v61, v[22:23], off offset:1152
	v_add_co_u32_e32 v20, vcc, s2, v18
	global_load_dword v60, v[42:43], off offset:512
	global_load_dword v57, v[42:43], off offset:768
	global_load_dword v55, v[42:43], off offset:1024
	global_load_dword v53, v[42:43], off offset:1280
	global_load_dword v52, v[42:43], off offset:1536
	global_load_dword v51, v[42:43], off offset:1792
	global_load_dword v50, v[42:43], off offset:2048
	global_load_dword v48, v[42:43], off offset:2304
	v_addc_co_u32_e32 v21, vcc, 0, v19, vcc
	global_load_dword v47, v[42:43], off offset:2944
	global_load_dword v46, v[42:43], off offset:3200
	global_load_dword v45, v[42:43], off offset:3456
	global_load_dword v44, v[42:43], off offset:3712
	s_nop 0
	global_load_dword v43, v[20:21], off offset:896
	global_load_dword v42, v[20:21], off offset:1152
	global_load_dword v41, v[20:21], off offset:1408
	global_load_dword v3, v[20:21], off offset:1664
	s_waitcnt vmcnt(31)
	v_and_b32_e32 v21, 0xffff0000, v49
	v_lshlrev_b32_e32 v20, 16, v49
	v_pk_mul_f32 v[22:23], v[20:21], v[20:21]
	s_nop 0
	v_add_f32_e32 v22, v22, v23
	v_mov_b32_e32 v23, v22
	s_nop 1
	v_permlane16_swap_b32_e32 v22, v23
	v_add_f32_e32 v22, v22, v23
	s_nop 1
	v_add_f32_dpp v22, v22, v22 row_ror:8 row_mask:0xf bank_mask:0xf
	s_nop 1
	v_add_f32_dpp v22, v22, v22 row_ror:4 row_mask:0xf bank_mask:0xf
	s_nop 1
	v_add_f32_dpp v22, v22, v22 quad_perm:[2,3,0,1] row_mask:0xf bank_mask:0xf
	s_nop 1
	v_add_f32_dpp v22, v22, v22 quad_perm:[1,0,3,2] row_mask:0xf bank_mask:0xf
	v_fmamk_f32 v22, v22, 0x3c800000, v170
	v_mul_f32_e32 v23, 0x4b800000, v22
	v_cmp_gt_f32_e32 vcc, s33, v22
	s_nop 1
	v_cndmask_b32_e32 v22, v22, v23, vcc
	v_rsq_f32_e32 v22, v22
	s_nop 0
	v_mul_f32_e32 v23, 0x45800000, v22
	v_cndmask_b32_e32 v22, v22, v23, vcc
	v_pk_mul_f32 v[22:23], v[4:5], v[22:23] op_sel_hi:[1,0]
	s_nop 0
	v_pk_mul_f32 v[22:23], v[22:23], v[20:21]
	ds_bpermute_b32 v20, v28, v22
	ds_bpermute_b32 v21, v28, v23
	s_and_saveexec_b64 s[2:3], s[12:13]
	s_xor_b64 s[18:19], exec, s[2:3]
	s_cbranch_execz .LBB0_154
	s_and_saveexec_b64 s[30:31], s[14:15]
	s_cbranch_execz .LBB0_153
	v_add_u32_e32 v49, 0, v35
	s_waitcnt lgkmcnt(0)
	v_pk_mul_f32 v[76:77], v[22:23], v[208:209]
	v_mul_f32_e32 v22, v209, v20
	v_mov_b32_e32 v20, v23
	v_pk_mul_f32 v[20:21], v[20:21], v[210:211]
	s_nop 0
	v_mov_b32_e32 v77, v20
	v_mov_b32_e32 v23, v21
	v_pk_add_f32 v[22:23], v[76:77], v[22:23]

; #define LAS __attribute__((address_space(3)))
; DI unsigned pk2(float lo, float hi) { f32x2 x = {lo, hi}; return __builtin_bit_cast(unsigned, __builtin_convertvector(x, bf16x2_t)); }
; DI float sum32(float v) { v += __shfl_xor(v, 16); return sum16(v); }
; DI f32x2 unpk(unsigned w) { f32x2 r = {bflo(w), bfhi(w)}; return r; }
; template <int HP> DI void rope2(f32x2& x, int hl, const LAS f32x2* cs) {
;   const float pa = __shfl_xor(x[0], HP), pb = __shfl_xor(x[1], HP);
;   if (hl < HP) { const f32x2 c0 = cs[2 * hl], c1 = cs[2 * hl + 1]; x[0] = x[0] * c0[0] - pa * c0[1]; x[1] = x[1] * c1[0] - pb * c1[1]; }
;   else if (hl < 2 * HP) { const f32x2 c0 = cs[2 * (hl - HP)], c1 = cs[2 * (hl - HP) + 1]; x[0] = x[0] * c0[0] + pa * c0[1]; x[1] = x[1] * c1[0] + pb * c1[1]; }
; DI void post_unit(const Params& p, int l, int unit, LAS unsigned char* lds) {
;     ...
;       f32x2 x = unpk(raw2[hf][s]); u16* pp = row + segcol[s] + 2 * lane;
;       if (s < 2) {
;         const float rs = rsqrtf(sum32(x[0] * x[0] + x[1] * x[1]) * (1.0f / 64.0f) + EPS);
;         x[0] *= rs * qna[2 * hl]; x[1] *= rs * qna[2 * hl + 1]; rope2<4>(x, hl, cs16 + t * 8);
;         x *= LOG2E * 0.125f; *(unsigned*)pp = pk2(x[0], x[1]);
.LBB0_154:
	s_or_saveexec_b64 s[18:19], s[18:19]
	v_add_u32_e32 v49, 0, v35
	s_xor_b64 exec, exec, s[18:19]
	s_cbranch_execz .LBB0_156
	s_waitcnt lgkmcnt(0)
	v_pk_mul_f32 v[76:77], v[22:23], v[212:213]
	v_mul_f32_e32 v22, v213, v20
	v_mov_b32_e32 v20, v23
	v_pk_mul_f32 v[20:21], v[20:21], v[214:215]
	s_nop 0
	v_mov_b32_e32 v77, v20
	v_mov_b32_e32 v23, v21
	v_pk_add_f32 v[22:23], v[76:77], v[22:23] neg_lo:[0,1] neg_hi:[0,1]
.LBB0_156:
	s_or_b64 exec, exec, s[18:19]
	s_mov_b64 s[2:3], 0xa000000
	s_waitcnt lgkmcnt(0)
	v_lshl_add_u64 v[20:21], v[18:19], 0, s[2:3]
	s_mov_b32 s2, 0x3e38aa3b
	v_pk_mul_f32 v[22:23], v[22:23], s[2:3] op_sel_hi:[1,0]
	s_nop 0
	v_cvt_pk_bf16_f32 v22, v22, v23
	global_store_dword v[20:21], v22, off
	s_waitcnt vmcnt(25)
	v_and_b32_e32 v21, 0xffff0000, v71
	v_lshlrev_b32_e32 v20, 16, v71
	v_pk_mul_f32 v[22:23], v[20:21], v[20:21]
	s_nop 0
	v_add_f32_e32 v22, v22, v23
	v_mov_b32_e32 v23, v22
	s_nop 1
	v_permlane16_swap_b32_e32 v22, v23
	v_add_f32_e32 v22, v22, v23
	s_nop 1
	v_add_f32_dpp v22, v22, v22 row_ror:8 row_mask:0xf bank_mask:0xf
	s_nop 1
	v_add_f32_dpp v22, v22, v22 row_ror:4 row_mask:0xf bank_mask:0xf
	s_nop 1
	v_add_f32_dpp v22, v22, v22 quad_perm:[2,3,0,1] row_mask:0xf bank_mask:0xf
	s_nop 1
	v_add_f32_dpp v22, v22, v22 quad_perm:[1,0,3,2] row_mask:0xf bank_mask:0xf
	v_fmamk_f32 v22, v22, 0x3c800000, v170
	v_cmp_gt_f32_e32 vcc, s33, v22
	v_mul_f32_e32 v23, 0x4b800000, v22
	s_nop 0
	v_cndmask_b32_e32 v22, v22, v23, vcc
	v_rsq_f32_e32 v22, v22
	s_nop 0
	v_mul_f32_e32 v23, 0x45800000, v22
	v_cndmask_b32_e32 v22, v22, v23, vcc
	v_pk_mul_f32 v[22:23], v[4:5], v[22:23] op_sel_hi:[1,0]
	s_nop 0
	v_pk_mul_f32 v[22:23], v[22:23], v[20:21]
	ds_bpermute_b32 v20, v28, v22
	ds_bpermute_b32 v21, v28, v23
	s_and_saveexec_b64 s[2:3], s[12:13]
	s_xor_b64 s[18:19], exec, s[2:3]
	s_cbranch_execz .LBB0_160
	s_and_saveexec_b64 s[30:31], s[14:15]
	s_cbranch_execz .LBB0_159
	s_waitcnt lgkmcnt(0)
	v_pk_mul_f32 v[76:77], v[22:23], v[208:209]
	v_mul_f32_e32 v22, v209, v20
	v_mov_b32_e32 v20, v23
	v_pk_mul_f32 v[20:21], v[20:21], v[210:211]
	s_nop 0
	v_mov_b32_e32 v77, v20
	v_mov_b32_e32 v23, v21
	v_pk_add_f32 v[22:23], v[76:77], v[22:23]

; #define LAS __attribute__((address_space(3)))
; DI unsigned pk2(float lo, float hi) { f32x2 x = {lo, hi}; return __builtin_bit_cast(unsigned, __builtin_convertvector(x, bf16x2_t)); }
; DI float sum32(float v) { v += __shfl_xor(v, 16); return sum16(v); }
; DI float sum64(float v) { v += __shfl_xor(v, 32); return sum32(v); }
; DI f32x2 unpk(unsigned w) { f32x2 r = {bflo(w), bfhi(w)}; return r; }
; template <int HP> DI void rope2(f32x2& x, int hl, const LAS f32x2* cs) {
;   const float pa = __shfl_xor(x[0], HP), pb = __shfl_xor(x[1], HP);
;   if (hl < HP) { const f32x2 c0 = cs[2 * hl], c1 = cs[2 * hl + 1]; x[0] = x[0] * c0[0] - pa * c0[1]; x[1] = x[1] * c1[0] - pb * c1[1]; }
;   else if (hl < 2 * HP) { const f32x2 c0 = cs[2 * (hl - HP)], c1 = cs[2 * (hl - HP) + 1]; x[0] = x[0] * c0[0] + pa * c0[1]; x[1] = x[1] * c1[0] + pb * c1[1]; }
; DI void post_unit(const Params& p, int l, int unit, LAS unsigned char* lds) {
;     ...
;       f32x2 x = unpk(raw2[hf][s]); u16* pp = row + segcol[s] + 2 * lane;
;       if (s < 2) {
;         const float rs = rsqrtf(sum32(x[0] * x[0] + x[1] * x[1]) * (1.0f / 64.0f) + EPS);
;         x[0] *= rs * qna[2 * hl]; x[1] *= rs * qna[2 * hl + 1]; rope2<4>(x, hl, cs16 + t * 8);
;         x *= LOG2E * 0.125f; *(unsigned*)pp = pk2(x[0], x[1]);
;       } else if (s == 2) {
;         const float rs = rsqrtf(sum64(x[0] * x[0] + x[1] * x[1]) * (1.0f / 128.0f) + EPS);
;         *(LAS unsigned*)(At + t * 272 + lane * 4) = pk2(x[0] * rs, x[1] * rs);
;       } else if (s < 7) {
;         rope2<4>(x, hl, cs16 + t * 8); *(unsigned*)pp = pk2(x[0], x[1]);
.LBB0_160:
	s_andn2_saveexec_b64 s[18:19], s[18:19]
	s_cbranch_execz .LBB0_162
	s_waitcnt lgkmcnt(0)
	v_pk_mul_f32 v[76:77], v[22:23], v[212:213]
	v_mul_f32_e32 v22, v213, v20
	v_mov_b32_e32 v20, v23
	v_pk_mul_f32 v[20:21], v[20:21], v[214:215]
	s_nop 0
	v_mov_b32_e32 v77, v20
	v_mov_b32_e32 v23, v21
	v_pk_add_f32 v[22:23], v[76:77], v[22:23] neg_lo:[0,1] neg_hi:[0,1]
.LBB0_162:
	s_or_b64 exec, exec, s[18:19]
	s_mov_b64 s[2:3], 0xa000100
	s_waitcnt lgkmcnt(0)
	v_lshl_add_u64 v[20:21], v[18:19], 0, s[2:3]
	s_mov_b32 s2, 0x3e38aa3b
	v_pk_mul_f32 v[22:23], v[22:23], s[2:3] op_sel_hi:[1,0]
	s_nop 0
	v_cvt_pk_bf16_f32 v22, v22, v23
	global_store_dword v[20:21], v22, off
	v_lshlrev_b32_e32 v20, 16, v59
	v_and_b32_e32 v21, 0xffff0000, v59
	v_pk_mul_f32 v[22:23], v[20:21], v[20:21]
	v_add_u32_e32 v59, 0, v33
	v_add_f32_e32 v22, v22, v23
	v_mov_b32_e32 v23, v22
	s_nop 1
	v_permlane32_swap_b32_e32 v22, v23
	v_add_f32_e32 v22, v22, v23
	v_mov_b32_e32 v23, v22
	s_nop 1
	v_permlane16_swap_b32_e32 v22, v23
	v_add_f32_e32 v22, v22, v23
	s_nop 1
	v_add_f32_dpp v22, v22, v22 row_ror:8 row_mask:0xf bank_mask:0xf
	s_nop 1
	v_add_f32_dpp v22, v22, v22 row_ror:4 row_mask:0xf bank_mask:0xf
	s_nop 1
	v_add_f32_dpp v22, v22, v22 quad_perm:[2,3,0,1] row_mask:0xf bank_mask:0xf
	s_nop 1
	v_add_f32_dpp v22, v22, v22 quad_perm:[1,0,3,2] row_mask:0xf bank_mask:0xf
	v_fmamk_f32 v22, v22, 0x3c000000, v170
	v_cmp_gt_f32_e32 vcc, s33, v22
	v_mul_f32_e32 v23, 0x4b800000, v22
	s_nop 0
	v_cndmask_b32_e32 v22, v22, v23, vcc
	v_rsq_f32_e32 v22, v22
	s_nop 0
	v_mul_f32_e32 v23, 0x45800000, v22
	v_cndmask_b32_e32 v22, v22, v23, vcc
	v_pk_mul_f32 v[20:21], v[22:23], v[20:21] op_sel_hi:[0,1]
	v_cvt_pk_bf16_f32 v20, v20, v21
	ds_write_b32 v59, v20
	v_lshlrev_b32_e32 v20, 16, v70
	v_and_b32_e32 v21, 0xffff0000, v70
	ds_bpermute_b32 v70, v28, v20
	ds_bpermute_b32 v23, v28, v21
	s_and_saveexec_b64 s[2:3], s[12:13]
	s_xor_b64 s[18:19], exec, s[2:3]
	s_cbranch_execz .LBB0_166
	s_and_saveexec_b64 s[30:31], s[14:15]
	s_cbranch_execz .LBB0_165
	v_mov_b32_e32 v22, v21
	s_waitcnt lgkmcnt(0)
	v_pk_mul_f32 v[22:23], v[210:211], v[22:23]
	v_mul_f32_e32 v20, v208, v20
	v_mul_f32_e32 v70, v209, v70
	v_mov_b32_e32 v21, v22
	v_mov_b32_e32 v71, v23
	v_pk_add_f32 v[20:21], v[20:21], v[70:71]

; #define LAS __attribute__((address_space(3)))
; DI unsigned pk2(float lo, float hi) { f32x2 x = {lo, hi}; return __builtin_bit_cast(unsigned, __builtin_convertvector(x, bf16x2_t)); }
; template <int HP> DI void rope2(f32x2& x, int hl, const LAS f32x2* cs) {
;   const float pa = __shfl_xor(x[0], HP), pb = __shfl_xor(x[1], HP);
;   if (hl < HP) { const f32x2 c0 = cs[2 * hl], c1 = cs[2 * hl + 1]; x[0] = x[0] * c0[0] - pa * c0[1]; x[1] = x[1] * c1[0] - pb * c1[1]; }
;   else if (hl < 2 * HP) { const f32x2 c0 = cs[2 * (hl - HP)], c1 = cs[2 * (hl - HP) + 1]; x[0] = x[0] * c0[0] + pa * c0[1]; x[1] = x[1] * c1[0] + pb * c1[1]; }
; DI void post_unit(const Params& p, int l, int unit, LAS unsigned char* lds) {
;     ...
;       } else if (s < 7) {
;         rope2<4>(x, hl, cs16 + t * 8); *(unsigned*)pp = pk2(x[0], x[1]);
.LBB0_166:
	s_andn2_saveexec_b64 s[18:19], s[18:19]
	s_cbranch_execz .LBB0_168
	v_mov_b32_e32 v22, v21
	s_waitcnt lgkmcnt(0)
	v_pk_mul_f32 v[22:23], v[214:215], v[22:23]
	v_mul_f32_e32 v20, v212, v20
	v_mul_f32_e32 v70, v213, v70
	v_mov_b32_e32 v21, v22
	v_mov_b32_e32 v71, v23
	v_pk_add_f32 v[20:21], v[20:21], v[70:71] neg_lo:[0,1] neg_hi:[0,1]
.LBB0_168:
	s_or_b64 exec, exec, s[18:19]
	s_mov_b64 s[2:3], 0xa000300
	s_waitcnt lgkmcnt(0)
	v_lshl_add_u64 v[22:23], v[18:19], 0, s[2:3]
	v_cvt_pk_bf16_f32 v20, v20, v21
	global_store_dword v[22:23], v20, off
	v_lshlrev_b32_e32 v20, 16, v69
	v_and_b32_e32 v21, 0xffff0000, v69
	ds_bpermute_b32 v69, v28, v20
	ds_bpermute_b32 v23, v28, v21
	s_and_saveexec_b64 s[2:3], s[12:13]
	s_xor_b64 s[18:19], exec, s[2:3]
	s_cbranch_execz .LBB0_172
	s_and_saveexec_b64 s[30:31], s[14:15]
	s_cbranch_execz .LBB0_171
	v_mov_b32_e32 v22, v21
	s_waitcnt lgkmcnt(0)
	v_pk_mul_f32 v[22:23], v[210:211], v[22:23]
	v_mul_f32_e32 v20, v208, v20
	v_mul_f32_e32 v70, v209, v69
	v_mov_b32_e32 v21, v22
	v_mov_b32_e32 v71, v23
	v_pk_add_f32 v[20:21], v[20:21], v[70:71]

; #define LAS __attribute__((address_space(3)))
; DI unsigned pk2(float lo, float hi) { f32x2 x = {lo, hi}; return __builtin_bit_cast(unsigned, __builtin_convertvector(x, bf16x2_t)); }
; template <int HP> DI void rope2(f32x2& x, int hl, const LAS f32x2* cs) {
;   const float pa = __shfl_xor(x[0], HP), pb = __shfl_xor(x[1], HP);
;   if (hl < HP) { const f32x2 c0 = cs[2 * hl], c1 = cs[2 * hl + 1]; x[0] = x[0] * c0[0] - pa * c0[1]; x[1] = x[1] * c1[0] - pb * c1[1]; }
;   else if (hl < 2 * HP) { const f32x2 c0 = cs[2 * (hl - HP)], c1 = cs[2 * (hl - HP) + 1]; x[0] = x[0] * c0[0] + pa * c0[1]; x[1] = x[1] * c1[0] + pb * c1[1]; }
; DI void post_unit(const Params& p, int l, int unit, LAS unsigned char* lds) {
;     ...
;       } else if (s < 7) {
;         rope2<4>(x, hl, cs16 + t * 8); *(unsigned*)pp = pk2(x[0], x[1]);
.LBB0_172:
	s_andn2_saveexec_b64 s[18:19], s[18:19]
	s_cbranch_execz .LBB0_174
	v_mov_b32_e32 v22, v21
	s_waitcnt lgkmcnt(0)
	v_pk_mul_f32 v[22:23], v[214:215], v[22:23]
	v_mul_f32_e32 v20, v212, v20
	v_mul_f32_e32 v70, v213, v69
	v_mov_b32_e32 v21, v22
	v_mov_b32_e32 v71, v23
	v_pk_add_f32 v[20:21], v[20:21], v[70:71] neg_lo:[0,1] neg_hi:[0,1]
.LBB0_174:
	s_or_b64 exec, exec, s[18:19]
	s_mov_b64 s[2:3], 0xa000400
	s_waitcnt lgkmcnt(0)
	v_lshl_add_u64 v[22:23], v[18:19], 0, s[2:3]
	v_cvt_pk_bf16_f32 v20, v20, v21
	global_store_dword v[22:23], v20, off
	v_lshlrev_b32_e32 v20, 16, v68
	v_and_b32_e32 v21, 0xffff0000, v68
	ds_bpermute_b32 v68, v28, v20
	ds_bpermute_b32 v23, v28, v21
	s_and_saveexec_b64 s[2:3], s[12:13]
	s_xor_b64 s[18:19], exec, s[2:3]
	s_cbranch_execz .LBB0_178
	s_and_saveexec_b64 s[30:31], s[14:15]
	s_cbranch_execz .LBB0_177
	v_mov_b32_e32 v22, v21
	s_waitcnt lgkmcnt(0)
	v_pk_mul_f32 v[22:23], v[210:211], v[22:23]
	v_mul_f32_e32 v20, v208, v20
	v_mul_f32_e32 v68, v209, v68
	v_mov_b32_e32 v21, v22
	v_mov_b32_e32 v69, v23
	v_pk_add_f32 v[20:21], v[20:21], v[68:69]

; #define LAS __attribute__((address_space(3)))
; DI unsigned pk2(float lo, float hi) { f32x2 x = {lo, hi}; return __builtin_bit_cast(unsigned, __builtin_convertvector(x, bf16x2_t)); }
; template <int HP> DI void rope2(f32x2& x, int hl, const LAS f32x2* cs) {
;   const float pa = __shfl_xor(x[0], HP), pb = __shfl_xor(x[1], HP);
;   if (hl < HP) { const f32x2 c0 = cs[2 * hl], c1 = cs[2 * hl + 1]; x[0] = x[0] * c0[0] - pa * c0[1]; x[1] = x[1] * c1[0] - pb * c1[1]; }
;   else if (hl < 2 * HP) { const f32x2 c0 = cs[2 * (hl - HP)], c1 = cs[2 * (hl - HP) + 1]; x[0] = x[0] * c0[0] + pa * c0[1]; x[1] = x[1] * c1[0] + pb * c1[1]; }
; DI void post_unit(const Params& p, int l, int unit, LAS unsigned char* lds) {
;     ...
;       } else if (s < 7) {
;         rope2<4>(x, hl, cs16 + t * 8); *(unsigned*)pp = pk2(x[0], x[1]);
.LBB0_178:
	s_andn2_saveexec_b64 s[18:19], s[18:19]
	s_cbranch_execz .LBB0_180
	v_mov_b32_e32 v22, v21
	s_waitcnt lgkmcnt(0)
	v_pk_mul_f32 v[22:23], v[214:215], v[22:23]
	v_mul_f32_e32 v20, v212, v20
	v_mul_f32_e32 v68, v213, v68
	v_mov_b32_e32 v21, v22
	v_mov_b32_e32 v69, v23
	v_pk_add_f32 v[20:21], v[20:21], v[68:69] neg_lo:[0,1] neg_hi:[0,1]
.LBB0_180:
	s_or_b64 exec, exec, s[18:19]
	s_mov_b64 s[2:3], 0xa000500
	s_waitcnt lgkmcnt(0)
	v_lshl_add_u64 v[22:23], v[18:19], 0, s[2:3]
	v_cvt_pk_bf16_f32 v20, v20, v21
	global_store_dword v[22:23], v20, off
	v_lshlrev_b32_e32 v20, 16, v67
	v_and_b32_e32 v21, 0xffff0000, v67
	ds_bpermute_b32 v67, v28, v20
	ds_bpermute_b32 v23, v28, v21
	s_and_saveexec_b64 s[2:3], s[12:13]
	s_xor_b64 s[18:19], exec, s[2:3]
	s_cbranch_execz .LBB0_184
	s_and_saveexec_b64 s[30:31], s[14:15]
	s_cbranch_execz .LBB0_183
	v_mov_b32_e32 v22, v21
	s_waitcnt lgkmcnt(0)
	v_pk_mul_f32 v[22:23], v[210:211], v[22:23]
	v_mul_f32_e32 v20, v208, v20
	v_mul_f32_e32 v68, v209, v67
	v_mov_b32_e32 v21, v22
	v_mov_b32_e32 v69, v23
	v_pk_add_f32 v[20:21], v[20:21], v[68:69]

; #define LAS __attribute__((address_space(3)))
; DI unsigned pk2(float lo, float hi) { f32x2 x = {lo, hi}; return __builtin_bit_cast(unsigned, __builtin_convertvector(x, bf16x2_t)); }
; DI float sum32(float v) { v += __shfl_xor(v, 16); return sum16(v); }
; template <int HP> DI void rope2(f32x2& x, int hl, const LAS f32x2* cs) {
;   const float pa = __shfl_xor(x[0], HP), pb = __shfl_xor(x[1], HP);
;   if (hl < HP) { const f32x2 c0 = cs[2 * hl], c1 = cs[2 * hl + 1]; x[0] = x[0] * c0[0] - pa * c0[1]; x[1] = x[1] * c1[0] - pb * c1[1]; }
;   else if (hl < 2 * HP) { const f32x2 c0 = cs[2 * (hl - HP)], c1 = cs[2 * (hl - HP) + 1]; x[0] = x[0] * c0[0] + pa * c0[1]; x[1] = x[1] * c1[0] + pb * c1[1]; }
; DI void post_unit(const Params& p, int l, int unit, LAS unsigned char* lds) {
;     ...
;       } else if (s < 7) {
;         rope2<4>(x, hl, cs16 + t * 8); *(unsigned*)pp = pk2(x[0], x[1]);
;       } else if (s == 7) {
;         const float rs = rsqrtf(sum32(x[0] * x[0] + x[1] * x[1]) * (1.0f / 64.0f) + EPS);
;         x *= rs; rope2<4>(x, hl, cs16 + t * 8); if (lane < 32) *(unsigned*)((u16*)(p.ws + WS_KIC) + (tok0 + t) * 64 + 2 * lane) = pk2(x[0], x[1]);
.LBB0_184:
	s_andn2_saveexec_b64 s[18:19], s[18:19]
	s_cbranch_execz .LBB0_186
	v_mov_b32_e32 v22, v21
	s_waitcnt lgkmcnt(0)
	v_pk_mul_f32 v[22:23], v[214:215], v[22:23]
	v_mul_f32_e32 v20, v212, v20
	v_mul_f32_e32 v68, v213, v67
	v_mov_b32_e32 v21, v22
	v_mov_b32_e32 v69, v23
	v_pk_add_f32 v[20:21], v[20:21], v[68:69] neg_lo:[0,1] neg_hi:[0,1]
.LBB0_186:
	s_or_b64 exec, exec, s[18:19]
	s_mov_b64 s[2:3], 0xa000600
	s_waitcnt lgkmcnt(0)
	v_lshl_add_u64 v[22:23], v[18:19], 0, s[2:3]
	v_cvt_pk_bf16_f32 v20, v20, v21
	global_store_dword v[22:23], v20, off
	v_lshlrev_b32_e32 v20, 16, v58
	v_and_b32_e32 v21, 0xffff0000, v58
	v_pk_mul_f32 v[22:23], v[20:21], v[20:21]
	s_nop 0
	v_add_f32_e32 v22, v22, v23
	v_mov_b32_e32 v23, v22
	s_nop 1
	v_permlane16_swap_b32_e32 v22, v23
	v_add_f32_e32 v22, v22, v23
	s_nop 1
	v_add_f32_dpp v22, v22, v22 row_ror:8 row_mask:0xf bank_mask:0xf
	s_nop 1
	v_add_f32_dpp v22, v22, v22 row_ror:4 row_mask:0xf bank_mask:0xf
	s_nop 1
	v_add_f32_dpp v22, v22, v22 quad_perm:[2,3,0,1] row_mask:0xf bank_mask:0xf
	s_nop 1
	v_add_f32_dpp v22, v22, v22 quad_perm:[1,0,3,2] row_mask:0xf bank_mask:0xf
	v_fmamk_f32 v22, v22, 0x3c800000, v170
	v_cmp_gt_f32_e32 vcc, s33, v22
	v_mul_f32_e32 v23, 0x4b800000, v22
	s_nop 0
	v_cndmask_b32_e32 v22, v22, v23, vcc
	v_rsq_f32_e32 v22, v22
	s_nop 0
	v_mul_f32_e32 v23, 0x45800000, v22
	v_cndmask_b32_e32 v22, v22, v23, vcc
	v_pk_mul_f32 v[20:21], v[22:23], v[20:21] op_sel_hi:[0,1]
	ds_bpermute_b32 v22, v28, v20
	ds_bpermute_b32 v23, v28, v21
	s_and_saveexec_b64 s[2:3], s[12:13]
	s_xor_b64 s[18:19], exec, s[2:3]
	s_cbranch_execz .LBB0_314
	s_and_saveexec_b64 s[30:31], s[14:15]
	s_cbranch_execz .LBB0_189
	s_waitcnt lgkmcnt(0)
	v_pk_mul_f32 v[72:73], v[20:21], v[208:209]
	v_mul_f32_e32 v20, v209, v22
	v_mov_b32_e32 v22, v21
	v_pk_mul_f32 v[22:23], v[210:211], v[22:23]
	s_nop 0
	v_mov_b32_e32 v73, v22
	v_mov_b32_e32 v21, v23
	v_pk_add_f32 v[20:21], v[72:73], v[20:21]

; #define LAS __attribute__((address_space(3)))
; DI unsigned pk2(float lo, float hi) { f32x2 x = {lo, hi}; return __builtin_bit_cast(unsigned, __builtin_convertvector(x, bf16x2_t)); }
; template <int HP> DI void rope2(f32x2& x, int hl, const LAS f32x2* cs) {
;   const float pa = __shfl_xor(x[0], HP), pb = __shfl_xor(x[1], HP);
;   if (hl < HP) { const f32x2 c0 = cs[2 * hl], c1 = cs[2 * hl + 1]; x[0] = x[0] * c0[0] - pa * c0[1]; x[1] = x[1] * c1[0] - pb * c1[1]; }
;   else if (hl < 2 * HP) { const f32x2 c0 = cs[2 * (hl - HP)], c1 = cs[2 * (hl - HP) + 1]; x[0] = x[0] * c0[0] + pa * c0[1]; x[1] = x[1] * c1[0] + pb * c1[1]; }
; DI void post_unit(const Params& p, int l, int unit, LAS unsigned char* lds) {
;     ...
;       } else if (s < 12) {
;         rope2<16>(x, hl, cs64 + t * 32);
;         const int hd = ((s & 1) ? 2 : 0) + hsel;
;         const float lg = log1pf(-exp2f(-5.0f - (float)hd));
;         const float f = (s < 10) ? expf(lg * (float)(t + 1)) : expf(lg * (float)(63 - t)) * 0.125f;
;         x *= f; *(unsigned*)pp = pk2(x[0], x[1]);
.LBB0_192:
	s_or_b64 exec, exec, s[18:19]
	s_waitcnt vmcnt(29)
	v_lshlrev_b32_e32 v58, 16, v56
	s_waitcnt lgkmcnt(1)
	v_and_b32_e32 v22, 0xffff0000, v56
	ds_bpermute_b32 v67, v26, v58
	s_waitcnt lgkmcnt(1)
	ds_bpermute_b32 v23, v26, v22
	v_add_u32_e32 v56, 0, v39
	s_and_saveexec_b64 s[2:3], s[10:11]
	s_xor_b64 s[18:19], exec, s[2:3]
	s_cbranch_execz .LBB0_194
	s_waitcnt lgkmcnt(0)
	v_pk_mul_f32 v[22:23], v[218:219], v[22:23]
	v_mul_f32_e32 v20, v216, v58
	v_mul_f32_e32 v68, v217, v67
	v_mov_b32_e32 v21, v22
	v_mov_b32_e32 v69, v23
	v_pk_add_f32 v[20:21], v[20:21], v[68:69]
.LBB0_194:
	s_andn2_saveexec_b64 s[18:19], s[18:19]
	s_cbranch_execz .LBB0_196
	s_waitcnt lgkmcnt(0)
	v_pk_mul_f32 v[22:23], v[222:223], v[22:23]
	v_mul_f32_e32 v20, v220, v58
	v_mul_f32_e32 v68, v221, v67
	v_mov_b32_e32 v21, v22
	v_mov_b32_e32 v69, v23
	v_pk_add_f32 v[20:21], v[20:21], v[68:69] neg_lo:[0,1] neg_hi:[0,1]
.LBB0_196:
	s_or_b64 exec, exec, s[18:19]
	v_add_u32_e32 v58, s36, v2
	s_waitcnt lgkmcnt(1)
	v_add_u32_e32 v67, 1, v58
	v_cvt_f32_i32_e32 v67, v67
	s_mov_b64 s[2:3], 0xa000980
	s_waitcnt lgkmcnt(0)
	v_lshl_add_u64 v[22:23], v[18:19], 0, s[2:3]
	v_mul_f32_e32 v68, v31, v67
	v_mul_f32_e32 v69, 0x3fb8aa3b, v68
	v_fma_f32 v70, v68, s64, -v69
	v_rndne_f32_e32 v71, v69
	v_fmac_f32_e32 v70, 0x32a5705f, v68
	v_sub_f32_e32 v69, v69, v71
	v_add_f32_e32 v69, v69, v70
	v_exp_f32_e32 v69, v69
	v_cvt_i32_f32_e32 v70, v71
	v_cmp_ngt_f32_e32 vcc, s65, v68
	v_ldexp_f32 v69, v69, v70
	s_nop 0
	v_cndmask_b32_e32 v69, 0, v69, vcc
	v_cmp_nlt_f32_e32 vcc, s89, v68
	s_nop 1
	v_cndmask_b32_e32 v68, v177, v69, vcc
	v_pk_mul_f32 v[20:21], v[68:69], v[20:21] op_sel_hi:[0,1]
	v_cvt_pk_bf16_f32 v20, v20, v21
	global_store_dword v[22:23], v20, off
	s_waitcnt vmcnt(29)
	v_lshlrev_b32_e32 v68, 16, v66
	v_and_b32_e32 v20, 0xffff0000, v66
	ds_bpermute_b32 v66, v26, v68
	ds_bpermute_b32 v21, v26, v20
	s_and_saveexec_b64 s[2:3], s[10:11]
	s_xor_b64 s[18:19], exec, s[2:3]
	s_cbranch_execz .LBB0_198
	s_waitcnt lgkmcnt(0)
	v_pk_mul_f32 v[20:21], v[218:219], v[20:21]
	v_mul_f32_e32 v22, v216, v68
	v_mul_f32_e32 v68, v217, v66
	v_mov_b32_e32 v23, v20
	v_mov_b32_e32 v69, v21
	v_pk_add_f32 v[22:23], v[22:23], v[68:69]
.LBB0_198:
	s_andn2_saveexec_b64 s[18:19], s[18:19]
	s_cbranch_execz .LBB0_200
	s_waitcnt lgkmcnt(0)
	v_pk_mul_f32 v[20:21], v[222:223], v[20:21]
	v_mul_f32_e32 v22, v220, v68
	v_mul_f32_e32 v68, v221, v66
	v_mov_b32_e32 v23, v20
	v_mov_b32_e32 v69, v21
	v_pk_add_f32 v[22:23], v[22:23], v[68:69] neg_lo:[0,1] neg_hi:[0,1]
.LBB0_200:
	s_or_b64 exec, exec, s[18:19]
	s_waitcnt lgkmcnt(1)
	v_mul_f32_e32 v66, v32, v67
	v_mul_f32_e32 v67, 0x3fb8aa3b, v66
	v_fma_f32 v68, v66, s64, -v67
	v_rndne_f32_e32 v69, v67
	v_fmac_f32_e32 v68, 0x32a5705f, v66
	v_sub_f32_e32 v67, v67, v69
	v_add_f32_e32 v67, v67, v68
	v_exp_f32_e32 v67, v67
	v_cvt_i32_f32_e32 v68, v69
	v_cmp_ngt_f32_e32 vcc, s65, v66
	s_mov_b64 s[2:3], 0xa000a80
	s_waitcnt lgkmcnt(0)
	v_lshl_add_u64 v[20:21], v[18:19], 0, s[2:3]
	v_ldexp_f32 v67, v67, v68
	v_cndmask_b32_e32 v67, 0, v67, vcc
	v_cmp_nlt_f32_e32 vcc, s89, v66
	s_nop 1
	v_cndmask_b32_e32 v66, v177, v67, vcc
	v_pk_mul_f32 v[22:23], v[66:67], v[22:23] op_sel_hi:[0,1]
	v_cvt_pk_bf16_f32 v22, v22, v23
	global_store_dword v[20:21], v22, off
	s_waitcnt vmcnt(29)
	v_lshlrev_b32_e32 v66, 16, v65
	v_and_b32_e32 v22, 0xffff0000, v65
	ds_bpermute_b32 v65, v26, v66
	ds_bpermute_b32 v23, v26, v22
	s_and_saveexec_b64 s[2:3], s[10:11]
	s_xor_b64 s[18:19], exec, s[2:3]
	s_cbranch_execz .LBB0_202
	s_waitcnt lgkmcnt(0)
	v_pk_mul_f32 v[22:23], v[218:219], v[22:23]
	v_mul_f32_e32 v20, v216, v66
	v_mul_f32_e32 v66, v217, v65
	v_mov_b32_e32 v21, v22
	v_mov_b32_e32 v67, v23
	v_pk_add_f32 v[20:21], v[20:21], v[66:67]
.LBB0_202:
	s_andn2_saveexec_b64 s[18:19], s[18:19]
	s_cbranch_execz .LBB0_204
	s_waitcnt lgkmcnt(0)
	v_pk_mul_f32 v[22:23], v[222:223], v[22:23]
	v_mul_f32_e32 v20, v220, v66
	v_mul_f32_e32 v66, v221, v65
	v_mov_b32_e32 v21, v22
	v_mov_b32_e32 v67, v23
	v_pk_add_f32 v[20:21], v[20:21], v[66:67] neg_lo:[0,1] neg_hi:[0,1]
; #define LAS __attribute__((address_space(3)))
; DI unsigned pk2(float lo, float hi) { f32x2 x = {lo, hi}; return __builtin_bit_cast(unsigned, __builtin_convertvector(x, bf16x2_t)); }
; DI float sum16(float v) { v += __shfl_xor(v, 8); v += __shfl_xor(v, 4); v += __shfl_xor(v, 2); v += __shfl_xor(v, 1); return v; }
; template <int HP> DI void rope2(f32x2& x, int hl, const LAS f32x2* cs) {
;   const float pa = __shfl_xor(x[0], HP), pb = __shfl_xor(x[1], HP);
;   if (hl < HP) { const f32x2 c0 = cs[2 * hl], c1 = cs[2 * hl + 1]; x[0] = x[0] * c0[0] - pa * c0[1]; x[1] = x[1] * c1[0] - pb * c1[1]; }
;   else if (hl < 2 * HP) { const f32x2 c0 = cs[2 * (hl - HP)], c1 = cs[2 * (hl - HP) + 1]; x[0] = x[0] * c0[0] + pa * c0[1]; x[1] = x[1] * c1[0] + pb * c1[1]; }
; DI void post_unit(const Params& p, int l, int unit, LAS unsigned char* lds) {
;     ...
;       } else if (s < 12) {
;         rope2<16>(x, hl, cs64 + t * 32);
;         const int hd = ((s & 1) ? 2 : 0) + hsel;
;         const float lg = log1pf(-exp2f(-5.0f - (float)hd));
;         const float f = (s < 10) ? expf(lg * (float)(t + 1)) : expf(lg * (float)(63 - t)) * 0.125f;
;         x *= f; *(unsigned*)pp = pk2(x[0], x[1]);
;       } else {
;         const float* gn = (s < 14) ? qnc : knc;
;         const float rs = rsqrtf(sum16(x[0] * x[0] + x[1] * x[1]) * (1.0f / 32.0f) + EPS);
;         x[0] *= rs * gn[2 * hl16]; x[1] *= rs * gn[2 * hl16 + 1]; rope2<2>(x, hl16, cs8 + t * 4);
;         if (s < 14) x *= LOG2E * 0.17677669529663687f;
;         *(unsigned*)pp = pk2(x[0], x[1]);
.LBB0_204:
	s_or_b64 exec, exec, s[18:19]
	s_waitcnt lgkmcnt(1)
	v_add_u32_e32 v65, 1, v38
	v_cvt_f32_i32_e32 v65, v65
	s_mov_b64 s[2:3], 0xa000b80
	s_waitcnt lgkmcnt(0)
	v_lshl_add_u64 v[22:23], v[18:19], 0, s[2:3]
	v_mul_f32_e32 v66, v31, v65
	v_mul_f32_e32 v67, 0x3fb8aa3b, v66
	v_fma_f32 v68, v66, s64, -v67
	v_rndne_f32_e32 v69, v67
	v_fmac_f32_e32 v68, 0x32a5705f, v66
	v_sub_f32_e32 v67, v67, v69
	v_add_f32_e32 v67, v67, v68
	v_exp_f32_e32 v67, v67
	v_cvt_i32_f32_e32 v68, v69
	v_cmp_ngt_f32_e32 vcc, s65, v66
	v_ldexp_f32 v67, v67, v68
	s_nop 0
	v_cndmask_b32_e32 v67, 0, v67, vcc
	v_cmp_nlt_f32_e32 vcc, s89, v66
	s_nop 1
	v_cndmask_b32_e32 v66, v177, v67, vcc
	v_mul_f32_e32 v66, 0x3e000000, v66
	v_pk_mul_f32 v[20:21], v[66:67], v[20:21] op_sel_hi:[0,1]
	v_cvt_pk_bf16_f32 v20, v20, v21
	global_store_dword v[22:23], v20, off
	s_waitcnt vmcnt(29)
	v_lshlrev_b32_e32 v66, 16, v64
	v_and_b32_e32 v20, 0xffff0000, v64
	ds_bpermute_b32 v64, v26, v66
	ds_bpermute_b32 v21, v26, v20
	s_and_saveexec_b64 s[2:3], s[10:11]
	s_xor_b64 s[18:19], exec, s[2:3]
	s_cbranch_execz .LBB0_206
	s_waitcnt lgkmcnt(0)
	v_pk_mul_f32 v[20:21], v[218:219], v[20:21]
	v_mul_f32_e32 v22, v216, v66
	v_mul_f32_e32 v66, v217, v64
	v_mov_b32_e32 v23, v20
	v_mov_b32_e32 v67, v21
	v_pk_add_f32 v[22:23], v[22:23], v[66:67]
.LBB0_206:
	s_andn2_saveexec_b64 s[18:19], s[18:19]
	s_cbranch_execz .LBB0_208
	s_waitcnt lgkmcnt(0)
	v_pk_mul_f32 v[20:21], v[222:223], v[20:21]
	v_mul_f32_e32 v22, v220, v66
	v_mul_f32_e32 v66, v221, v64
	v_mov_b32_e32 v23, v20
	v_mov_b32_e32 v67, v21
	v_pk_add_f32 v[22:23], v[22:23], v[66:67] neg_lo:[0,1] neg_hi:[0,1]
.LBB0_208:
	s_or_b64 exec, exec, s[18:19]
	s_waitcnt lgkmcnt(1)
	v_mul_f32_e32 v64, v32, v65
	v_mul_f32_e32 v65, 0x3fb8aa3b, v64
	v_fma_f32 v66, v64, s64, -v65
	v_rndne_f32_e32 v67, v65
	v_fmac_f32_e32 v66, 0x32a5705f, v64
	v_sub_f32_e32 v65, v65, v67
	v_add_f32_e32 v65, v65, v66
	v_exp_f32_e32 v65, v65
	v_cvt_i32_f32_e32 v66, v67
	v_cmp_ngt_f32_e32 vcc, s65, v64
	s_mov_b64 s[2:3], 0xa000c80
	s_waitcnt lgkmcnt(0)
	v_lshl_add_u64 v[20:21], v[18:19], 0, s[2:3]
	v_ldexp_f32 v65, v65, v66
	v_cndmask_b32_e32 v65, 0, v65, vcc
	v_cmp_nlt_f32_e32 vcc, s89, v64
	s_nop 1
	v_cndmask_b32_e32 v64, v177, v65, vcc
	v_mul_f32_e32 v64, 0x3e000000, v64
	v_pk_mul_f32 v[22:23], v[64:65], v[22:23] op_sel_hi:[0,1]
	v_cvt_pk_bf16_f32 v22, v22, v23
	global_store_dword v[20:21], v22, off
	s_waitcnt vmcnt(29)
	v_lshlrev_b32_e32 v20, 16, v54
	v_and_b32_e32 v21, 0xffff0000, v54
	v_pk_mul_f32 v[22:23], v[20:21], v[20:21]
	s_nop 0
	v_add_f32_e32 v22, v22, v23
	s_nop 1
	v_add_f32_dpp v22, v22, v22 row_ror:8 row_mask:0xf bank_mask:0xf
	s_nop 1
	v_add_f32_dpp v22, v22, v22 row_ror:4 row_mask:0xf bank_mask:0xf
	s_nop 1
	v_add_f32_dpp v22, v22, v22 quad_perm:[2,3,0,1] row_mask:0xf bank_mask:0xf
	s_nop 1
	v_add_f32_dpp v22, v22, v22 quad_perm:[1,0,3,2] row_mask:0xf bank_mask:0xf
	v_fmamk_f32 v22, v22, 0x3d000000, v170
	v_cmp_gt_f32_e32 vcc, s33, v22
	v_mul_f32_e32 v23, 0x4b800000, v22
	s_nop 0
	v_cndmask_b32_e32 v22, v22, v23, vcc
	v_rsq_f32_e32 v22, v22
	s_nop 0
	v_mul_f32_e32 v23, 0x45800000, v22
	v_cndmask_b32_e32 v22, v22, v23, vcc
	v_pk_mul_f32 v[22:23], v[6:7], v[22:23] op_sel_hi:[1,0]
	s_nop 0
	v_pk_mul_f32 v[22:23], v[22:23], v[20:21]
	ds_bpermute_b32 v20, v29, v22
	ds_bpermute_b32 v21, v29, v23
	s_and_saveexec_b64 s[2:3], s[6:7]
	s_xor_b64 s[18:19], exec, s[2:3]
	s_cbranch_execz .LBB0_212
	s_and_saveexec_b64 s[30:31], s[8:9]
	s_cbranch_execz .LBB0_211
	v_add_u32_e32 v54, 0, v40
	s_waitcnt lgkmcnt(0)
	v_pk_mul_f32 v[68:69], v[22:23], v[224:225]
	v_mul_f32_e32 v22, v225, v20
	v_mov_b32_e32 v20, v23
	v_pk_mul_f32 v[20:21], v[20:21], v[226:227]
	s_nop 0
	v_mov_b32_e32 v69, v20
	v_mov_b32_e32 v23, v21
	v_pk_add_f32 v[22:23], v[68:69], v[22:23]

; #define LAS __attribute__((address_space(3)))
; DI unsigned pk2(float lo, float hi) { f32x2 x = {lo, hi}; return __builtin_bit_cast(unsigned, __builtin_convertvector(x, bf16x2_t)); }
; DI float sum16(float v) { v += __shfl_xor(v, 8); v += __shfl_xor(v, 4); v += __shfl_xor(v, 2); v += __shfl_xor(v, 1); return v; }
; template <int HP> DI void rope2(f32x2& x, int hl, const LAS f32x2* cs) {
;   const float pa = __shfl_xor(x[0], HP), pb = __shfl_xor(x[1], HP);
;   if (hl < HP) { const f32x2 c0 = cs[2 * hl], c1 = cs[2 * hl + 1]; x[0] = x[0] * c0[0] - pa * c0[1]; x[1] = x[1] * c1[0] - pb * c1[1]; }
;   else if (hl < 2 * HP) { const f32x2 c0 = cs[2 * (hl - HP)], c1 = cs[2 * (hl - HP) + 1]; x[0] = x[0] * c0[0] + pa * c0[1]; x[1] = x[1] * c1[0] + pb * c1[1]; }
; DI void post_unit(const Params& p, int l, int unit, LAS unsigned char* lds) {
;     ...
;       } else {
;         const float* gn = (s < 14) ? qnc : knc;
;         const float rs = rsqrtf(sum16(x[0] * x[0] + x[1] * x[1]) * (1.0f / 32.0f) + EPS);
;         x[0] *= rs * gn[2 * hl16]; x[1] *= rs * gn[2 * hl16 + 1]; rope2<2>(x, hl16, cs8 + t * 4);
;         if (s < 14) x *= LOG2E * 0.17677669529663687f;
;         *(unsigned*)pp = pk2(x[0], x[1]);
.LBB0_212:
	s_or_saveexec_b64 s[18:19], s[18:19]
	v_add_u32_e32 v54, 0, v40
	s_xor_b64 exec, exec, s[18:19]
	s_cbranch_execz .LBB0_214
	s_waitcnt lgkmcnt(0)
	v_pk_mul_f32 v[68:69], v[22:23], v[228:229]
	v_mul_f32_e32 v22, v229, v20
	v_mov_b32_e32 v20, v23
	v_pk_mul_f32 v[20:21], v[20:21], v[230:231]
	s_nop 0
	v_mov_b32_e32 v69, v20
	v_mov_b32_e32 v23, v21
	v_pk_add_f32 v[22:23], v[68:69], v[22:23] neg_lo:[0,1] neg_hi:[0,1]
.LBB0_214:
	s_or_b64 exec, exec, s[18:19]
	s_mov_b64 s[2:3], 0xa001180
	s_waitcnt lgkmcnt(0)
	v_lshl_add_u64 v[20:21], v[18:19], 0, s[2:3]
	s_mov_b32 s2, 0x3e8293ee
	v_pk_mul_f32 v[22:23], v[22:23], s[2:3] op_sel_hi:[1,0]
	s_nop 0
	v_cvt_pk_bf16_f32 v22, v22, v23
	global_store_dword v[20:21], v22, off
	s_waitcnt vmcnt(29)
	v_lshlrev_b32_e32 v20, 16, v63
	v_and_b32_e32 v21, 0xffff0000, v63
	v_pk_mul_f32 v[22:23], v[20:21], v[20:21]
	s_nop 0
	v_add_f32_e32 v22, v22, v23
	s_nop 1
	v_add_f32_dpp v22, v22, v22 row_ror:8 row_mask:0xf bank_mask:0xf
	s_nop 1
	v_add_f32_dpp v22, v22, v22 row_ror:4 row_mask:0xf bank_mask:0xf
	s_nop 1
	v_add_f32_dpp v22, v22, v22 quad_perm:[2,3,0,1] row_mask:0xf bank_mask:0xf
	s_nop 1
	v_add_f32_dpp v22, v22, v22 quad_perm:[1,0,3,2] row_mask:0xf bank_mask:0xf
	v_fmamk_f32 v22, v22, 0x3d000000, v170
	v_cmp_gt_f32_e32 vcc, s33, v22
	v_mul_f32_e32 v23, 0x4b800000, v22
	s_nop 0
	v_cndmask_b32_e32 v22, v22, v23, vcc
	v_rsq_f32_e32 v22, v22
	s_nop 0
	v_mul_f32_e32 v23, 0x45800000, v22
	v_cndmask_b32_e32 v22, v22, v23, vcc
	v_pk_mul_f32 v[22:23], v[6:7], v[22:23] op_sel_hi:[1,0]
	s_nop 0
	v_pk_mul_f32 v[22:23], v[22:23], v[20:21]
	ds_bpermute_b32 v20, v29, v22
	ds_bpermute_b32 v21, v29, v23
	s_and_saveexec_b64 s[2:3], s[6:7]
	s_xor_b64 s[18:19], exec, s[2:3]
	s_cbranch_execz .LBB0_218
	s_and_saveexec_b64 s[30:31], s[8:9]
	s_cbranch_execz .LBB0_217
	s_waitcnt lgkmcnt(0)
	v_pk_mul_f32 v[68:69], v[22:23], v[224:225]
	v_mul_f32_e32 v22, v225, v20
	v_mov_b32_e32 v20, v23
	v_pk_mul_f32 v[20:21], v[20:21], v[226:227]
	s_nop 0
	v_mov_b32_e32 v69, v20
	v_mov_b32_e32 v23, v21
	v_pk_add_f32 v[22:23], v[68:69], v[22:23]

; #define LAS __attribute__((address_space(3)))
; DI unsigned pk2(float lo, float hi) { f32x2 x = {lo, hi}; return __builtin_bit_cast(unsigned, __builtin_convertvector(x, bf16x2_t)); }
; DI float sum16(float v) { v += __shfl_xor(v, 8); v += __shfl_xor(v, 4); v += __shfl_xor(v, 2); v += __shfl_xor(v, 1); return v; }
; template <int HP> DI void rope2(f32x2& x, int hl, const LAS f32x2* cs) {
;   const float pa = __shfl_xor(x[0], HP), pb = __shfl_xor(x[1], HP);
;   if (hl < HP) { const f32x2 c0 = cs[2 * hl], c1 = cs[2 * hl + 1]; x[0] = x[0] * c0[0] - pa * c0[1]; x[1] = x[1] * c1[0] - pb * c1[1]; }
;   else if (hl < 2 * HP) { const f32x2 c0 = cs[2 * (hl - HP)], c1 = cs[2 * (hl - HP) + 1]; x[0] = x[0] * c0[0] + pa * c0[1]; x[1] = x[1] * c1[0] + pb * c1[1]; }
; DI void post_unit(const Params& p, int l, int unit, LAS unsigned char* lds) {
;     ...
;       } else {
;         const float* gn = (s < 14) ? qnc : knc;
;         const float rs = rsqrtf(sum16(x[0] * x[0] + x[1] * x[1]) * (1.0f / 32.0f) + EPS);
;         x[0] *= rs * gn[2 * hl16]; x[1] *= rs * gn[2 * hl16 + 1]; rope2<2>(x, hl16, cs8 + t * 4);
;         if (s < 14) x *= LOG2E * 0.17677669529663687f;
;         *(unsigned*)pp = pk2(x[0], x[1]);
.LBB0_218:
	s_andn2_saveexec_b64 s[18:19], s[18:19]
	s_cbranch_execz .LBB0_220
	s_waitcnt lgkmcnt(0)
	v_pk_mul_f32 v[68:69], v[22:23], v[228:229]
	v_mul_f32_e32 v22, v229, v20
	v_mov_b32_e32 v20, v23
	v_pk_mul_f32 v[20:21], v[20:21], v[230:231]
	s_nop 0
	v_mov_b32_e32 v69, v20
	v_mov_b32_e32 v23, v21
	v_pk_add_f32 v[22:23], v[68:69], v[22:23] neg_lo:[0,1] neg_hi:[0,1]
.LBB0_220:
	s_or_b64 exec, exec, s[18:19]
	s_mov_b64 s[2:3], 0xa001280
	s_waitcnt lgkmcnt(0)
	v_lshl_add_u64 v[20:21], v[18:19], 0, s[2:3]
	s_mov_b32 s2, 0x3e8293ee
	v_pk_mul_f32 v[22:23], v[22:23], s[2:3] op_sel_hi:[1,0]
	s_nop 0
	v_cvt_pk_bf16_f32 v22, v22, v23
	global_store_dword v[20:21], v22, off
	s_waitcnt vmcnt(29)
	v_lshlrev_b32_e32 v20, 16, v62
	v_and_b32_e32 v21, 0xffff0000, v62
	v_pk_mul_f32 v[22:23], v[20:21], v[20:21]
	s_nop 0
	v_add_f32_e32 v22, v22, v23
	s_nop 1
	v_add_f32_dpp v22, v22, v22 row_ror:8 row_mask:0xf bank_mask:0xf
	s_nop 1
	v_add_f32_dpp v22, v22, v22 row_ror:4 row_mask:0xf bank_mask:0xf
	s_nop 1
	v_add_f32_dpp v22, v22, v22 quad_perm:[2,3,0,1] row_mask:0xf bank_mask:0xf
	s_nop 1
	v_add_f32_dpp v22, v22, v22 quad_perm:[1,0,3,2] row_mask:0xf bank_mask:0xf
	v_fmamk_f32 v22, v22, 0x3d000000, v170
	v_cmp_gt_f32_e32 vcc, s33, v22
	v_mul_f32_e32 v23, 0x4b800000, v22
	s_nop 0
	v_cndmask_b32_e32 v22, v22, v23, vcc
	v_rsq_f32_e32 v22, v22
	s_nop 0
	v_mul_f32_e32 v23, 0x45800000, v22
	v_cndmask_b32_e32 v22, v22, v23, vcc
	v_pk_mul_f32 v[22:23], v[8:9], v[22:23] op_sel_hi:[1,0]
	s_nop 0
	v_pk_mul_f32 v[22:23], v[22:23], v[20:21]
	ds_bpermute_b32 v20, v29, v22
	ds_bpermute_b32 v21, v29, v23
	s_and_saveexec_b64 s[2:3], s[6:7]
	s_xor_b64 s[18:19], exec, s[2:3]
	s_cbranch_execz .LBB0_224
	s_and_saveexec_b64 s[30:31], s[8:9]
	s_cbranch_execz .LBB0_223
	s_waitcnt lgkmcnt(0)
	v_pk_mul_f32 v[66:67], v[22:23], v[224:225]
	v_mul_f32_e32 v22, v225, v20
	v_mov_b32_e32 v20, v23
	v_pk_mul_f32 v[20:21], v[20:21], v[226:227]
	s_nop 0
	v_mov_b32_e32 v67, v20
	v_mov_b32_e32 v23, v21
	v_pk_add_f32 v[22:23], v[66:67], v[22:23]

; #define LAS __attribute__((address_space(3)))
; DI unsigned pk2(float lo, float hi) { f32x2 x = {lo, hi}; return __builtin_bit_cast(unsigned, __builtin_convertvector(x, bf16x2_t)); }
; DI float sum16(float v) { v += __shfl_xor(v, 8); v += __shfl_xor(v, 4); v += __shfl_xor(v, 2); v += __shfl_xor(v, 1); return v; }
; template <int HP> DI void rope2(f32x2& x, int hl, const LAS f32x2* cs) {
;   const float pa = __shfl_xor(x[0], HP), pb = __shfl_xor(x[1], HP);
;   if (hl < HP) { const f32x2 c0 = cs[2 * hl], c1 = cs[2 * hl + 1]; x[0] = x[0] * c0[0] - pa * c0[1]; x[1] = x[1] * c1[0] - pb * c1[1]; }
;   else if (hl < 2 * HP) { const f32x2 c0 = cs[2 * (hl - HP)], c1 = cs[2 * (hl - HP) + 1]; x[0] = x[0] * c0[0] + pa * c0[1]; x[1] = x[1] * c1[0] + pb * c1[1]; }
; DI void post_unit(const Params& p, int l, int unit, LAS unsigned char* lds) {
;     ...
;       } else {
;         const float* gn = (s < 14) ? qnc : knc;
;         const float rs = rsqrtf(sum16(x[0] * x[0] + x[1] * x[1]) * (1.0f / 32.0f) + EPS);
;         x[0] *= rs * gn[2 * hl16]; x[1] *= rs * gn[2 * hl16 + 1]; rope2<2>(x, hl16, cs8 + t * 4);
;         if (s < 14) x *= LOG2E * 0.17677669529663687f;
;         *(unsigned*)pp = pk2(x[0], x[1]);
.LBB0_224:
	s_andn2_saveexec_b64 s[18:19], s[18:19]
	s_cbranch_execz .LBB0_226
	s_waitcnt lgkmcnt(0)
	v_pk_mul_f32 v[66:67], v[22:23], v[228:229]
	v_mul_f32_e32 v22, v229, v20
	v_mov_b32_e32 v20, v23
	v_pk_mul_f32 v[20:21], v[20:21], v[230:231]
	s_nop 0
	v_mov_b32_e32 v67, v20
	v_mov_b32_e32 v23, v21
	v_pk_add_f32 v[22:23], v[66:67], v[22:23] neg_lo:[0,1] neg_hi:[0,1]
.LBB0_226:
	s_or_b64 exec, exec, s[18:19]
	s_mov_b64 s[2:3], 0xa001380
	s_waitcnt lgkmcnt(0)
	v_lshl_add_u64 v[20:21], v[18:19], 0, s[2:3]
	v_cvt_pk_bf16_f32 v22, v22, v23
	global_store_dword v[20:21], v22, off
	s_waitcnt vmcnt(29)
	v_lshlrev_b32_e32 v20, 16, v61
	v_and_b32_e32 v21, 0xffff0000, v61
	v_pk_mul_f32 v[22:23], v[20:21], v[20:21]
	s_nop 0
	v_add_f32_e32 v22, v22, v23
	s_nop 1
	v_add_f32_dpp v22, v22, v22 row_ror:8 row_mask:0xf bank_mask:0xf
	s_nop 1
	v_add_f32_dpp v22, v22, v22 row_ror:4 row_mask:0xf bank_mask:0xf
	s_nop 1
	v_add_f32_dpp v22, v22, v22 quad_perm:[2,3,0,1] row_mask:0xf bank_mask:0xf
	s_nop 1
	v_add_f32_dpp v22, v22, v22 quad_perm:[1,0,3,2] row_mask:0xf bank_mask:0xf
	v_fmamk_f32 v22, v22, 0x3d000000, v170
	v_cmp_gt_f32_e32 vcc, s33, v22
	v_mul_f32_e32 v23, 0x4b800000, v22
	s_nop 0
	v_cndmask_b32_e32 v22, v22, v23, vcc
	v_rsq_f32_e32 v22, v22
	s_nop 0
	v_mul_f32_e32 v23, 0x45800000, v22
	v_cndmask_b32_e32 v22, v22, v23, vcc
	v_pk_mul_f32 v[22:23], v[8:9], v[22:23] op_sel_hi:[1,0]
	s_nop 0
	v_pk_mul_f32 v[22:23], v[22:23], v[20:21]
	ds_bpermute_b32 v20, v29, v22
	ds_bpermute_b32 v21, v29, v23
	s_and_saveexec_b64 s[2:3], s[6:7]
	s_xor_b64 s[18:19], exec, s[2:3]
	s_cbranch_execz .LBB0_230
	s_and_saveexec_b64 s[30:31], s[8:9]
	s_cbranch_execz .LBB0_229
	s_waitcnt lgkmcnt(0)
	v_pk_mul_f32 v[66:67], v[22:23], v[224:225]
	v_mul_f32_e32 v22, v225, v20
	v_mov_b32_e32 v20, v23
	v_pk_mul_f32 v[20:21], v[20:21], v[226:227]
	s_nop 0
	v_mov_b32_e32 v67, v20
	v_mov_b32_e32 v23, v21
	v_pk_add_f32 v[22:23], v[66:67], v[22:23]

; #define LAS __attribute__((address_space(3)))
; DI unsigned pk2(float lo, float hi) { f32x2 x = {lo, hi}; return __builtin_bit_cast(unsigned, __builtin_convertvector(x, bf16x2_t)); }
; DI float sum32(float v) { v += __shfl_xor(v, 16); return sum16(v); }
; DI f32x2 unpk(unsigned w) { f32x2 r = {bflo(w), bfhi(w)}; return r; }
; template <int HP> DI void rope2(f32x2& x, int hl, const LAS f32x2* cs) {
;   const float pa = __shfl_xor(x[0], HP), pb = __shfl_xor(x[1], HP);
;   if (hl < HP) { const f32x2 c0 = cs[2 * hl], c1 = cs[2 * hl + 1]; x[0] = x[0] * c0[0] - pa * c0[1]; x[1] = x[1] * c1[0] - pb * c1[1]; }
;   else if (hl < 2 * HP) { const f32x2 c0 = cs[2 * (hl - HP)], c1 = cs[2 * (hl - HP) + 1]; x[0] = x[0] * c0[0] + pa * c0[1]; x[1] = x[1] * c1[0] + pb * c1[1]; }
; DI void post_unit(const Params& p, int l, int unit, LAS unsigned char* lds) {
;     ...
;       f32x2 x = unpk(raw2[hf][s]); u16* pp = row + segcol[s] + 2 * lane;
;       if (s < 2) {
;         const float rs = rsqrtf(sum32(x[0] * x[0] + x[1] * x[1]) * (1.0f / 64.0f) + EPS);
;         x[0] *= rs * qna[2 * hl]; x[1] *= rs * qna[2 * hl + 1]; rope2<4>(x, hl, cs16 + t * 8);
;         x *= LOG2E * 0.125f; *(unsigned*)pp = pk2(x[0], x[1]);
.LBB0_232:
	s_or_b64 exec, exec, s[18:19]
	s_mov_b64 s[2:3], 0xa001480
	v_lshl_add_u64 v[18:19], v[18:19], 0, s[2:3]
	s_waitcnt lgkmcnt(1)
	v_cvt_pk_bf16_f32 v20, v22, v23
	global_store_dword v[18:19], v20, off
	s_waitcnt vmcnt(29)
	v_and_b32_e32 v19, 0xffff0000, v60
	v_lshlrev_b32_e32 v18, 16, v60
	s_waitcnt lgkmcnt(0)
	v_pk_mul_f32 v[20:21], v[18:19], v[18:19]
	s_nop 0
	v_add_f32_e32 v20, v20, v21
	v_mov_b32_e32 v21, v20
	s_nop 1
	v_permlane16_swap_b32_e32 v20, v21
	v_add_f32_e32 v20, v20, v21
	s_nop 1
	v_add_f32_dpp v20, v20, v20 row_ror:8 row_mask:0xf bank_mask:0xf
	s_nop 1
	v_add_f32_dpp v20, v20, v20 row_ror:4 row_mask:0xf bank_mask:0xf
	s_nop 1
	v_add_f32_dpp v20, v20, v20 quad_perm:[2,3,0,1] row_mask:0xf bank_mask:0xf
	s_nop 1
	v_add_f32_dpp v20, v20, v20 quad_perm:[1,0,3,2] row_mask:0xf bank_mask:0xf
	v_fmamk_f32 v20, v20, 0x3c800000, v170
	v_cmp_gt_f32_e32 vcc, s33, v20
	v_mul_f32_e32 v21, 0x4b800000, v20
	s_nop 0
	v_cndmask_b32_e32 v20, v20, v21, vcc
	v_rsq_f32_e32 v20, v20
	s_nop 0
	v_mul_f32_e32 v21, 0x45800000, v20
	v_cndmask_b32_e32 v20, v20, v21, vcc
	v_pk_mul_f32 v[20:21], v[4:5], v[20:21] op_sel_hi:[1,0]
	s_nop 0
	v_pk_mul_f32 v[20:21], v[20:21], v[18:19]
	ds_bpermute_b32 v18, v28, v20
	ds_bpermute_b32 v19, v28, v21
	s_and_saveexec_b64 s[2:3], s[12:13]
	s_xor_b64 s[18:19], exec, s[2:3]
	s_cbranch_execz .LBB0_236
	s_and_saveexec_b64 s[30:31], s[14:15]
	s_cbranch_execz .LBB0_235
	s_waitcnt lgkmcnt(0)
	v_pk_mul_f32 v[22:23], v[20:21], v[212:213]
	v_mul_f32_e32 v20, v213, v18
	v_mov_b32_e32 v18, v21
	v_pk_mul_f32 v[18:19], v[18:19], v[214:215]
	s_nop 0
	v_mov_b32_e32 v23, v18
	v_mov_b32_e32 v21, v19
	v_pk_add_f32 v[20:21], v[22:23], v[20:21]

; #define LAS __attribute__((address_space(3)))
; DI unsigned pk2(float lo, float hi) { f32x2 x = {lo, hi}; return __builtin_bit_cast(unsigned, __builtin_convertvector(x, bf16x2_t)); }
; DI float sum32(float v) { v += __shfl_xor(v, 16); return sum16(v); }
; DI f32x2 unpk(unsigned w) { f32x2 r = {bflo(w), bfhi(w)}; return r; }
; template <int HP> DI void rope2(f32x2& x, int hl, const LAS f32x2* cs) {
;   const float pa = __shfl_xor(x[0], HP), pb = __shfl_xor(x[1], HP);
;   if (hl < HP) { const f32x2 c0 = cs[2 * hl], c1 = cs[2 * hl + 1]; x[0] = x[0] * c0[0] - pa * c0[1]; x[1] = x[1] * c1[0] - pb * c1[1]; }
;   else if (hl < 2 * HP) { const f32x2 c0 = cs[2 * (hl - HP)], c1 = cs[2 * (hl - HP) + 1]; x[0] = x[0] * c0[0] + pa * c0[1]; x[1] = x[1] * c1[0] + pb * c1[1]; }
; DI void post_unit(const Params& p, int l, int unit, LAS unsigned char* lds) {
;     ...
;       f32x2 x = unpk(raw2[hf][s]); u16* pp = row + segcol[s] + 2 * lane;
;       if (s < 2) {
;         const float rs = rsqrtf(sum32(x[0] * x[0] + x[1] * x[1]) * (1.0f / 64.0f) + EPS);
;         x[0] *= rs * qna[2 * hl]; x[1] *= rs * qna[2 * hl + 1]; rope2<4>(x, hl, cs16 + t * 8);
;         x *= LOG2E * 0.125f; *(unsigned*)pp = pk2(x[0], x[1]);
.LBB0_236:
	s_andn2_saveexec_b64 s[18:19], s[18:19]
	s_cbranch_execz .LBB0_238
	s_waitcnt lgkmcnt(0)
	v_pk_mul_f32 v[22:23], v[20:21], v[232:233]
	v_mul_f32_e32 v20, v233, v18
	v_mov_b32_e32 v18, v21
	v_pk_mul_f32 v[18:19], v[18:19], v[234:235]
	s_nop 0
	v_mov_b32_e32 v23, v18
	v_mov_b32_e32 v21, v19
	v_pk_add_f32 v[20:21], v[22:23], v[20:21] neg_lo:[0,1] neg_hi:[0,1]
.LBB0_238:
	s_or_b64 exec, exec, s[18:19]
	s_mov_b32 s2, 0x3e38aa3b
	s_waitcnt lgkmcnt(0)
	v_lshl_add_u64 v[18:19], v[14:15], 0, v[0:1]
	v_pk_mul_f32 v[20:21], v[20:21], s[2:3] op_sel_hi:[1,0]
	s_nop 0
	v_cvt_pk_bf16_f32 v22, v20, v21
	v_add_co_u32_e32 v20, vcc, 0xa002000, v18
	s_nop 1
	v_addc_co_u32_e32 v21, vcc, 0, v19, vcc
	global_store_dword v[20:21], v22, off offset:512
	s_waitcnt vmcnt(29)
	v_and_b32_e32 v21, 0xffff0000, v57
	v_lshlrev_b32_e32 v20, 16, v57
	v_pk_mul_f32 v[22:23], v[20:21], v[20:21]
	s_nop 0
	v_add_f32_e32 v22, v22, v23
	v_mov_b32_e32 v23, v22
	s_nop 1
	v_permlane16_swap_b32_e32 v22, v23
	v_add_f32_e32 v22, v22, v23
	s_nop 1
	v_add_f32_dpp v22, v22, v22 row_ror:8 row_mask:0xf bank_mask:0xf
	s_nop 1
	v_add_f32_dpp v22, v22, v22 row_ror:4 row_mask:0xf bank_mask:0xf
	s_nop 1
	v_add_f32_dpp v22, v22, v22 quad_perm:[2,3,0,1] row_mask:0xf bank_mask:0xf
	s_nop 1
	v_add_f32_dpp v22, v22, v22 quad_perm:[1,0,3,2] row_mask:0xf bank_mask:0xf
	v_fmamk_f32 v22, v22, 0x3c800000, v170
	v_cmp_gt_f32_e32 vcc, s33, v22
	v_mul_f32_e32 v23, 0x4b800000, v22
	s_nop 0
	v_cndmask_b32_e32 v22, v22, v23, vcc
	v_rsq_f32_e32 v22, v22
	s_nop 0
	v_mul_f32_e32 v23, 0x45800000, v22
	v_cndmask_b32_e32 v22, v22, v23, vcc
	v_pk_mul_f32 v[22:23], v[4:5], v[22:23] op_sel_hi:[1,0]
	s_nop 0
	v_pk_mul_f32 v[22:23], v[22:23], v[20:21]
	ds_bpermute_b32 v20, v28, v22
	ds_bpermute_b32 v21, v28, v23
	s_and_saveexec_b64 s[2:3], s[12:13]
	s_xor_b64 s[18:19], exec, s[2:3]
	s_cbranch_execz .LBB0_242
	s_and_saveexec_b64 s[30:31], s[14:15]
	s_cbranch_execz .LBB0_241
	s_waitcnt lgkmcnt(0)
	v_pk_mul_f32 v[64:65], v[22:23], v[212:213]
	v_mul_f32_e32 v22, v213, v20
	v_mov_b32_e32 v20, v23
	v_pk_mul_f32 v[20:21], v[20:21], v[214:215]
	s_nop 0
	v_mov_b32_e32 v65, v20
	v_mov_b32_e32 v23, v21
	v_pk_add_f32 v[22:23], v[64:65], v[22:23]

; #define LAS __attribute__((address_space(3)))
; DI unsigned pk2(float lo, float hi) { f32x2 x = {lo, hi}; return __builtin_bit_cast(unsigned, __builtin_convertvector(x, bf16x2_t)); }
; DI float sum32(float v) { v += __shfl_xor(v, 16); return sum16(v); }
; DI float sum64(float v) { v += __shfl_xor(v, 32); return sum32(v); }
; DI f32x2 unpk(unsigned w) { f32x2 r = {bflo(w), bfhi(w)}; return r; }
; template <int HP> DI void rope2(f32x2& x, int hl, const LAS f32x2* cs) {
;   const float pa = __shfl_xor(x[0], HP), pb = __shfl_xor(x[1], HP);
;   if (hl < HP) { const f32x2 c0 = cs[2 * hl], c1 = cs[2 * hl + 1]; x[0] = x[0] * c0[0] - pa * c0[1]; x[1] = x[1] * c1[0] - pb * c1[1]; }
;   else if (hl < 2 * HP) { const f32x2 c0 = cs[2 * (hl - HP)], c1 = cs[2 * (hl - HP) + 1]; x[0] = x[0] * c0[0] + pa * c0[1]; x[1] = x[1] * c1[0] + pb * c1[1]; }
; DI void post_unit(const Params& p, int l, int unit, LAS unsigned char* lds) {
;     ...
;       f32x2 x = unpk(raw2[hf][s]); u16* pp = row + segcol[s] + 2 * lane;
;       if (s < 2) {
;         const float rs = rsqrtf(sum32(x[0] * x[0] + x[1] * x[1]) * (1.0f / 64.0f) + EPS);
;         x[0] *= rs * qna[2 * hl]; x[1] *= rs * qna[2 * hl + 1]; rope2<4>(x, hl, cs16 + t * 8);
;         x *= LOG2E * 0.125f; *(unsigned*)pp = pk2(x[0], x[1]);
;       } else if (s == 2) {
;         const float rs = rsqrtf(sum64(x[0] * x[0] + x[1] * x[1]) * (1.0f / 128.0f) + EPS);
;         *(LAS unsigned*)(At + t * 272 + lane * 4) = pk2(x[0] * rs, x[1] * rs);
;       } else if (s < 7) {
;         rope2<4>(x, hl, cs16 + t * 8); *(unsigned*)pp = pk2(x[0], x[1]);
.LBB0_242:
	s_andn2_saveexec_b64 s[18:19], s[18:19]
	s_cbranch_execz .LBB0_244
	s_waitcnt lgkmcnt(0)
	v_pk_mul_f32 v[64:65], v[22:23], v[232:233]
	v_mul_f32_e32 v22, v233, v20
	v_mov_b32_e32 v20, v23
	v_pk_mul_f32 v[20:21], v[20:21], v[234:235]
	s_nop 0
	v_mov_b32_e32 v65, v20
	v_mov_b32_e32 v23, v21
	v_pk_add_f32 v[22:23], v[64:65], v[22:23] neg_lo:[0,1] neg_hi:[0,1]
.LBB0_244:
	s_or_b64 exec, exec, s[18:19]
	s_mov_b32 s2, 0x3e38aa3b
	s_waitcnt lgkmcnt(0)
	v_pk_mul_f32 v[20:21], v[22:23], s[2:3] op_sel_hi:[1,0]
	s_nop 0
	v_cvt_pk_bf16_f32 v22, v20, v21
	v_add_co_u32_e32 v20, vcc, 0xa002000, v18
	s_nop 1
	v_addc_co_u32_e32 v21, vcc, 0, v19, vcc
	global_store_dword v[20:21], v22, off offset:768
	s_waitcnt vmcnt(29)
	v_lshlrev_b32_e32 v20, 16, v55
	v_and_b32_e32 v21, 0xffff0000, v55
	v_pk_mul_f32 v[22:23], v[20:21], v[20:21]
	s_nop 0
	v_add_f32_e32 v22, v22, v23
	v_mov_b32_e32 v23, v22
	s_nop 1
	v_permlane32_swap_b32_e32 v22, v23
	v_add_f32_e32 v22, v22, v23
	v_mov_b32_e32 v23, v22
	s_nop 1
	v_permlane16_swap_b32_e32 v22, v23
	v_add_f32_e32 v22, v22, v23
	s_nop 1
	v_add_f32_dpp v22, v22, v22 row_ror:8 row_mask:0xf bank_mask:0xf
	s_nop 1
	v_add_f32_dpp v22, v22, v22 row_ror:4 row_mask:0xf bank_mask:0xf
	s_nop 1
	v_add_f32_dpp v22, v22, v22 quad_perm:[2,3,0,1] row_mask:0xf bank_mask:0xf
	s_nop 1
	v_add_f32_dpp v22, v22, v22 quad_perm:[1,0,3,2] row_mask:0xf bank_mask:0xf
	v_fmamk_f32 v22, v22, 0x3c000000, v170
	v_cmp_gt_f32_e32 vcc, s33, v22
	v_mul_f32_e32 v23, 0x4b800000, v22
	s_nop 0
	v_cndmask_b32_e32 v22, v22, v23, vcc
	v_rsq_f32_e32 v22, v22
	s_nop 0
	v_mul_f32_e32 v23, 0x45800000, v22
	v_cndmask_b32_e32 v22, v22, v23, vcc
	v_pk_mul_f32 v[20:21], v[22:23], v[20:21] op_sel_hi:[0,1]
	v_cvt_pk_bf16_f32 v20, v20, v21
	ds_write_b32 v59, v20 offset:272
	s_waitcnt vmcnt(28)
	v_lshlrev_b32_e32 v20, 16, v53
	v_and_b32_e32 v21, 0xffff0000, v53
	ds_bpermute_b32 v53, v28, v20
	ds_bpermute_b32 v23, v28, v21
	s_and_saveexec_b64 s[2:3], s[12:13]
	s_xor_b64 s[18:19], exec, s[2:3]
	s_cbranch_execz .LBB0_248
	s_and_saveexec_b64 s[30:31], s[14:15]
	s_cbranch_execz .LBB0_247
	v_mov_b32_e32 v22, v21
	s_waitcnt lgkmcnt(0)
	v_pk_mul_f32 v[22:23], v[214:215], v[22:23]
	v_mul_f32_e32 v20, v212, v20
	v_mul_f32_e32 v60, v213, v53
	v_mov_b32_e32 v21, v22
	v_mov_b32_e32 v61, v23
	v_pk_add_f32 v[20:21], v[20:21], v[60:61]

; #define LAS __attribute__((address_space(3)))
; DI unsigned pk2(float lo, float hi) { f32x2 x = {lo, hi}; return __builtin_bit_cast(unsigned, __builtin_convertvector(x, bf16x2_t)); }
; template <int HP> DI void rope2(f32x2& x, int hl, const LAS f32x2* cs) {
;   const float pa = __shfl_xor(x[0], HP), pb = __shfl_xor(x[1], HP);
;   if (hl < HP) { const f32x2 c0 = cs[2 * hl], c1 = cs[2 * hl + 1]; x[0] = x[0] * c0[0] - pa * c0[1]; x[1] = x[1] * c1[0] - pb * c1[1]; }
;   else if (hl < 2 * HP) { const f32x2 c0 = cs[2 * (hl - HP)], c1 = cs[2 * (hl - HP) + 1]; x[0] = x[0] * c0[0] + pa * c0[1]; x[1] = x[1] * c1[0] + pb * c1[1]; }
; DI void post_unit(const Params& p, int l, int unit, LAS unsigned char* lds) {
;     ...
;       } else if (s < 7) {
;         rope2<4>(x, hl, cs16 + t * 8); *(unsigned*)pp = pk2(x[0], x[1]);
.LBB0_248:
	s_andn2_saveexec_b64 s[18:19], s[18:19]
	s_cbranch_execz .LBB0_250
	v_mov_b32_e32 v22, v21
	s_waitcnt lgkmcnt(0)
	v_pk_mul_f32 v[22:23], v[234:235], v[22:23]
	v_mul_f32_e32 v20, v232, v20
	v_mul_f32_e32 v60, v233, v53
	v_mov_b32_e32 v21, v22
	v_mov_b32_e32 v61, v23
	v_pk_add_f32 v[20:21], v[20:21], v[60:61] neg_lo:[0,1] neg_hi:[0,1]
.LBB0_250:
	s_or_b64 exec, exec, s[18:19]
	v_cvt_pk_bf16_f32 v22, v20, v21
	v_add_co_u32_e32 v20, vcc, 0xa002000, v18
	s_nop 1
	v_addc_co_u32_e32 v21, vcc, 0, v19, vcc
	global_store_dword v[20:21], v22, off offset:1280
	s_waitcnt vmcnt(28)
	v_lshlrev_b32_e32 v20, 16, v52
	v_and_b32_e32 v21, 0xffff0000, v52
	ds_bpermute_b32 v52, v28, v20
	s_waitcnt lgkmcnt(1)
	ds_bpermute_b32 v23, v28, v21
	s_and_saveexec_b64 s[2:3], s[12:13]
	s_xor_b64 s[18:19], exec, s[2:3]
	s_cbranch_execz .LBB0_254
	s_and_saveexec_b64 s[30:31], s[14:15]
	s_cbranch_execz .LBB0_253
	v_mov_b32_e32 v22, v21
	s_waitcnt lgkmcnt(0)
	v_pk_mul_f32 v[22:23], v[214:215], v[22:23]
	v_mul_f32_e32 v20, v212, v20
	v_mul_f32_e32 v52, v213, v52
	v_mov_b32_e32 v21, v22
	v_mov_b32_e32 v53, v23
	v_pk_add_f32 v[20:21], v[20:21], v[52:53]

; #define LAS __attribute__((address_space(3)))
; DI unsigned pk2(float lo, float hi) { f32x2 x = {lo, hi}; return __builtin_bit_cast(unsigned, __builtin_convertvector(x, bf16x2_t)); }
; template <int HP> DI void rope2(f32x2& x, int hl, const LAS f32x2* cs) {
;   const float pa = __shfl_xor(x[0], HP), pb = __shfl_xor(x[1], HP);
;   if (hl < HP) { const f32x2 c0 = cs[2 * hl], c1 = cs[2 * hl + 1]; x[0] = x[0] * c0[0] - pa * c0[1]; x[1] = x[1] * c1[0] - pb * c1[1]; }
;   else if (hl < 2 * HP) { const f32x2 c0 = cs[2 * (hl - HP)], c1 = cs[2 * (hl - HP) + 1]; x[0] = x[0] * c0[0] + pa * c0[1]; x[1] = x[1] * c1[0] + pb * c1[1]; }
; DI void post_unit(const Params& p, int l, int unit, LAS unsigned char* lds) {
;     ...
;       } else if (s < 7) {
;         rope2<4>(x, hl, cs16 + t * 8); *(unsigned*)pp = pk2(x[0], x[1]);
.LBB0_254:
	s_andn2_saveexec_b64 s[18:19], s[18:19]
	s_cbranch_execz .LBB0_256
	v_mov_b32_e32 v22, v21
	s_waitcnt lgkmcnt(0)
	v_pk_mul_f32 v[22:23], v[234:235], v[22:23]
	v_mul_f32_e32 v20, v232, v20
	v_mul_f32_e32 v52, v233, v52
	v_mov_b32_e32 v21, v22
	v_mov_b32_e32 v53, v23
	v_pk_add_f32 v[20:21], v[20:21], v[52:53] neg_lo:[0,1] neg_hi:[0,1]
.LBB0_256:
	s_or_b64 exec, exec, s[18:19]
	v_cvt_pk_bf16_f32 v22, v20, v21
	v_add_co_u32_e32 v20, vcc, 0xa002000, v18
	s_nop 1
	v_addc_co_u32_e32 v21, vcc, 0, v19, vcc
	global_store_dword v[20:21], v22, off offset:1536
	s_waitcnt vmcnt(28)
	v_lshlrev_b32_e32 v20, 16, v51
	v_and_b32_e32 v21, 0xffff0000, v51
	ds_bpermute_b32 v51, v28, v20
	s_waitcnt lgkmcnt(1)
	ds_bpermute_b32 v23, v28, v21
	s_and_saveexec_b64 s[2:3], s[12:13]
	s_xor_b64 s[18:19], exec, s[2:3]
	s_cbranch_execz .LBB0_260
	s_and_saveexec_b64 s[30:31], s[14:15]
	s_cbranch_execz .LBB0_259
	v_mov_b32_e32 v22, v21
	s_waitcnt lgkmcnt(0)
	v_pk_mul_f32 v[22:23], v[214:215], v[22:23]
	v_mul_f32_e32 v20, v212, v20
	v_mul_f32_e32 v52, v213, v51
	v_mov_b32_e32 v21, v22
	v_mov_b32_e32 v53, v23
	v_pk_add_f32 v[20:21], v[20:21], v[52:53]

; #define LAS __attribute__((address_space(3)))
; DI unsigned pk2(float lo, float hi) { f32x2 x = {lo, hi}; return __builtin_bit_cast(unsigned, __builtin_convertvector(x, bf16x2_t)); }
; template <int HP> DI void rope2(f32x2& x, int hl, const LAS f32x2* cs) {
;   const float pa = __shfl_xor(x[0], HP), pb = __shfl_xor(x[1], HP);
;   if (hl < HP) { const f32x2 c0 = cs[2 * hl], c1 = cs[2 * hl + 1]; x[0] = x[0] * c0[0] - pa * c0[1]; x[1] = x[1] * c1[0] - pb * c1[1]; }
;   else if (hl < 2 * HP) { const f32x2 c0 = cs[2 * (hl - HP)], c1 = cs[2 * (hl - HP) + 1]; x[0] = x[0] * c0[0] + pa * c0[1]; x[1] = x[1] * c1[0] + pb * c1[1]; }
; DI void post_unit(const Params& p, int l, int unit, LAS unsigned char* lds) {
;     ...
;       } else if (s < 7) {
;         rope2<4>(x, hl, cs16 + t * 8); *(unsigned*)pp = pk2(x[0], x[1]);
.LBB0_260:
	s_andn2_saveexec_b64 s[18:19], s[18:19]
	s_cbranch_execz .LBB0_262
	v_mov_b32_e32 v22, v21
	s_waitcnt lgkmcnt(0)
	v_pk_mul_f32 v[22:23], v[234:235], v[22:23]
	v_mul_f32_e32 v20, v232, v20
	v_mul_f32_e32 v52, v233, v51
	v_mov_b32_e32 v21, v22
	v_mov_b32_e32 v53, v23
	v_pk_add_f32 v[20:21], v[20:21], v[52:53] neg_lo:[0,1] neg_hi:[0,1]
.LBB0_262:
	s_or_b64 exec, exec, s[18:19]
	v_cvt_pk_bf16_f32 v22, v20, v21
	v_add_co_u32_e32 v20, vcc, 0xa002000, v18
	s_nop 1
	v_addc_co_u32_e32 v21, vcc, 0, v19, vcc
	global_store_dword v[20:21], v22, off offset:1792
	s_waitcnt vmcnt(28)
	v_lshlrev_b32_e32 v20, 16, v50
	v_and_b32_e32 v21, 0xffff0000, v50
	ds_bpermute_b32 v50, v28, v20
	s_waitcnt lgkmcnt(1)
	ds_bpermute_b32 v23, v28, v21
	s_and_saveexec_b64 s[2:3], s[12:13]
	s_xor_b64 s[18:19], exec, s[2:3]
	s_cbranch_execz .LBB0_266
	s_and_saveexec_b64 s[30:31], s[14:15]
	s_cbranch_execz .LBB0_265
	v_mov_b32_e32 v22, v21
	s_waitcnt lgkmcnt(0)
	v_pk_mul_f32 v[22:23], v[214:215], v[22:23]
	v_mul_f32_e32 v20, v212, v20
	v_mul_f32_e32 v50, v213, v50
	v_mov_b32_e32 v21, v22
	v_mov_b32_e32 v51, v23
	v_pk_add_f32 v[20:21], v[20:21], v[50:51]

; #define LAS __attribute__((address_space(3)))
; DI unsigned pk2(float lo, float hi) { f32x2 x = {lo, hi}; return __builtin_bit_cast(unsigned, __builtin_convertvector(x, bf16x2_t)); }
; DI float sum32(float v) { v += __shfl_xor(v, 16); return sum16(v); }
; template <int HP> DI void rope2(f32x2& x, int hl, const LAS f32x2* cs) {
;   const float pa = __shfl_xor(x[0], HP), pb = __shfl_xor(x[1], HP);
;   if (hl < HP) { const f32x2 c0 = cs[2 * hl], c1 = cs[2 * hl + 1]; x[0] = x[0] * c0[0] - pa * c0[1]; x[1] = x[1] * c1[0] - pb * c1[1]; }
;   else if (hl < 2 * HP) { const f32x2 c0 = cs[2 * (hl - HP)], c1 = cs[2 * (hl - HP) + 1]; x[0] = x[0] * c0[0] + pa * c0[1]; x[1] = x[1] * c1[0] + pb * c1[1]; }
; DI void post_unit(const Params& p, int l, int unit, LAS unsigned char* lds) {
;     ...
;       } else if (s < 7) {
;         rope2<4>(x, hl, cs16 + t * 8); *(unsigned*)pp = pk2(x[0], x[1]);
;       } else if (s == 7) {
;         const float rs = rsqrtf(sum32(x[0] * x[0] + x[1] * x[1]) * (1.0f / 64.0f) + EPS);
;         x *= rs; rope2<4>(x, hl, cs16 + t * 8); if (lane < 32) *(unsigned*)((u16*)(p.ws + WS_KIC) + (tok0 + t) * 64 + 2 * lane) = pk2(x[0], x[1]);
.LBB0_266:
	s_andn2_saveexec_b64 s[18:19], s[18:19]
	s_cbranch_execz .LBB0_268
	v_mov_b32_e32 v22, v21
	s_waitcnt lgkmcnt(0)
	v_pk_mul_f32 v[22:23], v[234:235], v[22:23]
	v_mul_f32_e32 v20, v232, v20
	v_mul_f32_e32 v50, v233, v50
	v_mov_b32_e32 v21, v22
	v_mov_b32_e32 v51, v23
	v_pk_add_f32 v[20:21], v[20:21], v[50:51] neg_lo:[0,1] neg_hi:[0,1]
.LBB0_268:
	s_or_b64 exec, exec, s[18:19]
	v_cvt_pk_bf16_f32 v22, v20, v21
	v_add_co_u32_e32 v20, vcc, 0xa002000, v18
	s_nop 1
	v_addc_co_u32_e32 v21, vcc, 0, v19, vcc
	global_store_dword v[20:21], v22, off offset:2048
	s_waitcnt vmcnt(28)
	v_lshlrev_b32_e32 v20, 16, v48
	v_and_b32_e32 v21, 0xffff0000, v48
	s_waitcnt lgkmcnt(0)
	v_pk_mul_f32 v[22:23], v[20:21], v[20:21]
	s_nop 0
	v_add_f32_e32 v22, v22, v23
	v_mov_b32_e32 v23, v22
	s_nop 1
	v_permlane16_swap_b32_e32 v22, v23
	v_add_f32_e32 v22, v22, v23
	s_nop 1
	v_add_f32_dpp v22, v22, v22 row_ror:8 row_mask:0xf bank_mask:0xf
	s_nop 1
	v_add_f32_dpp v22, v22, v22 row_ror:4 row_mask:0xf bank_mask:0xf
	s_nop 1
	v_add_f32_dpp v22, v22, v22 quad_perm:[2,3,0,1] row_mask:0xf bank_mask:0xf
	s_nop 1
	v_add_f32_dpp v22, v22, v22 quad_perm:[1,0,3,2] row_mask:0xf bank_mask:0xf
	v_fmamk_f32 v22, v22, 0x3c800000, v170
	v_cmp_gt_f32_e32 vcc, s33, v22
	v_mul_f32_e32 v23, 0x4b800000, v22
	s_nop 0
	v_cndmask_b32_e32 v22, v22, v23, vcc
	v_rsq_f32_e32 v22, v22
	s_nop 0
	v_mul_f32_e32 v23, 0x45800000, v22
	v_cndmask_b32_e32 v22, v22, v23, vcc
	v_pk_mul_f32 v[20:21], v[22:23], v[20:21] op_sel_hi:[0,1]
	ds_bpermute_b32 v22, v28, v20
	ds_bpermute_b32 v23, v28, v21
	s_and_saveexec_b64 s[2:3], s[12:13]
	s_xor_b64 s[18:19], exec, s[2:3]
	s_cbranch_execz .LBB0_316
	s_and_saveexec_b64 s[30:31], s[14:15]
	s_cbranch_execz .LBB0_271
	s_waitcnt lgkmcnt(0)
	v_pk_mul_f32 v[52:53], v[20:21], v[212:213]
	v_mul_f32_e32 v20, v213, v22
	v_mov_b32_e32 v22, v21
	v_pk_mul_f32 v[22:23], v[214:215], v[22:23]
	s_nop 0
	v_mov_b32_e32 v53, v22
	v_mov_b32_e32 v21, v23
	v_pk_add_f32 v[20:21], v[52:53], v[20:21]

; #define LAS __attribute__((address_space(3)))
; DI unsigned pk2(float lo, float hi) { f32x2 x = {lo, hi}; return __builtin_bit_cast(unsigned, __builtin_convertvector(x, bf16x2_t)); }
; template <int HP> DI void rope2(f32x2& x, int hl, const LAS f32x2* cs) {
;   const float pa = __shfl_xor(x[0], HP), pb = __shfl_xor(x[1], HP);
;   if (hl < HP) { const f32x2 c0 = cs[2 * hl], c1 = cs[2 * hl + 1]; x[0] = x[0] * c0[0] - pa * c0[1]; x[1] = x[1] * c1[0] - pb * c1[1]; }
;   else if (hl < 2 * HP) { const f32x2 c0 = cs[2 * (hl - HP)], c1 = cs[2 * (hl - HP) + 1]; x[0] = x[0] * c0[0] + pa * c0[1]; x[1] = x[1] * c1[0] + pb * c1[1]; }
; DI void post_unit(const Params& p, int l, int unit, LAS unsigned char* lds) {
;     ...
;       } else if (s < 12) {
;         rope2<16>(x, hl, cs64 + t * 32);
;         const int hd = ((s & 1) ? 2 : 0) + hsel;
;         const float lg = log1pf(-exp2f(-5.0f - (float)hd));
;         const float f = (s < 10) ? expf(lg * (float)(t + 1)) : expf(lg * (float)(63 - t)) * 0.125f;
;         x *= f; *(unsigned*)pp = pk2(x[0], x[1]);
.LBB0_274:
	s_or_b64 exec, exec, s[18:19]
	s_waitcnt vmcnt(27)
	v_lshlrev_b32_e32 v48, 16, v47
	s_waitcnt lgkmcnt(1)
	v_and_b32_e32 v22, 0xffff0000, v47
	ds_bpermute_b32 v47, v26, v48
	s_waitcnt lgkmcnt(1)
	ds_bpermute_b32 v23, v26, v22
	s_and_saveexec_b64 s[2:3], s[10:11]
	s_xor_b64 s[18:19], exec, s[2:3]
	s_cbranch_execz .LBB0_276
	s_waitcnt lgkmcnt(0)
	v_pk_mul_f32 v[22:23], v[222:223], v[22:23]
	v_mul_f32_e32 v20, v220, v48
	v_mul_f32_e32 v48, v221, v47
	v_mov_b32_e32 v21, v22
	v_mov_b32_e32 v49, v23
	v_pk_add_f32 v[20:21], v[20:21], v[48:49]
.LBB0_276:
	s_andn2_saveexec_b64 s[18:19], s[18:19]
	s_cbranch_execz .LBB0_278
	s_waitcnt lgkmcnt(0)
	v_pk_mul_f32 v[22:23], v[238:239], v[22:23]
	v_mul_f32_e32 v20, v236, v48
	v_mul_f32_e32 v48, v237, v47
	v_mov_b32_e32 v21, v22
	v_mov_b32_e32 v49, v23
	v_pk_add_f32 v[20:21], v[20:21], v[48:49] neg_lo:[0,1] neg_hi:[0,1]
.LBB0_278:
	s_or_b64 exec, exec, s[18:19]
	v_add_u32_e32 v22, 2, v58
	s_waitcnt lgkmcnt(1)
	v_cvt_f32_i32_e32 v47, v22
	v_mul_f32_e32 v22, v31, v47
	s_waitcnt lgkmcnt(0)
	v_mul_f32_e32 v23, 0x3fb8aa3b, v22
	v_fma_f32 v48, v22, s64, -v23
	v_rndne_f32_e32 v49, v23
	v_fmac_f32_e32 v48, 0x32a5705f, v22
	v_sub_f32_e32 v23, v23, v49
	v_add_f32_e32 v23, v23, v48
	v_cvt_i32_f32_e32 v49, v49
	v_exp_f32_e32 v23, v23
	v_cmp_ngt_f32_e32 vcc, s65, v22
	s_waitcnt vmcnt(26)
	v_lshlrev_b32_e32 v48, 16, v46
	v_ldexp_f32 v23, v23, v49
	v_cndmask_b32_e32 v23, 0, v23, vcc
	v_cmp_nlt_f32_e32 vcc, s89, v22
	s_nop 1
	v_cndmask_b32_e32 v22, v177, v23, vcc
	v_pk_mul_f32 v[20:21], v[22:23], v[20:21] op_sel_hi:[0,1]
	v_and_b32_e32 v22, 0xffff0000, v46
	ds_bpermute_b32 v46, v26, v48
	ds_bpermute_b32 v23, v26, v22
	v_cvt_pk_bf16_f32 v49, v20, v21
	v_add_co_u32_e32 v20, vcc, 0xa002000, v18
	s_nop 1
	v_addc_co_u32_e32 v21, vcc, 0, v19, vcc
	global_store_dword v[20:21], v49, off offset:2944
	s_and_saveexec_b64 s[2:3], s[10:11]
	s_xor_b64 s[18:19], exec, s[2:3]
	s_cbranch_execz .LBB0_280
	s_waitcnt lgkmcnt(0)
	v_pk_mul_f32 v[22:23], v[222:223], v[22:23]
	v_mul_f32_e32 v20, v220, v48
	v_mul_f32_e32 v48, v221, v46
	v_mov_b32_e32 v21, v22
	v_mov_b32_e32 v49, v23
	v_pk_add_f32 v[20:21], v[20:21], v[48:49]
.LBB0_280:
	s_andn2_saveexec_b64 s[18:19], s[18:19]
	s_cbranch_execz .LBB0_282
	s_waitcnt lgkmcnt(0)
	v_pk_mul_f32 v[22:23], v[238:239], v[22:23]
	v_mul_f32_e32 v20, v236, v48
	v_mul_f32_e32 v48, v237, v46
	v_mov_b32_e32 v21, v22
	v_mov_b32_e32 v49, v23
	v_pk_add_f32 v[20:21], v[20:21], v[48:49] neg_lo:[0,1] neg_hi:[0,1]
.LBB0_282:
	s_or_b64 exec, exec, s[18:19]
	v_mul_f32_e32 v22, v32, v47
	s_waitcnt lgkmcnt(0)
	v_mul_f32_e32 v23, 0x3fb8aa3b, v22
	v_fma_f32 v46, v22, s64, -v23
	v_rndne_f32_e32 v47, v23
	v_fmac_f32_e32 v46, 0x32a5705f, v22
	v_sub_f32_e32 v23, v23, v47
	v_add_f32_e32 v23, v23, v46
	v_cvt_i32_f32_e32 v46, v47
	v_exp_f32_e32 v23, v23
	v_cmp_ngt_f32_e32 vcc, s65, v22
	v_ldexp_f32 v23, v23, v46
	s_nop 0
	v_cndmask_b32_e32 v23, 0, v23, vcc
	v_cmp_nlt_f32_e32 vcc, s89, v22
	s_waitcnt vmcnt(26)
	v_lshlrev_b32_e32 v46, 16, v45
	v_cndmask_b32_e32 v22, v177, v23, vcc
	v_pk_mul_f32 v[20:21], v[22:23], v[20:21] op_sel_hi:[0,1]
	v_and_b32_e32 v22, 0xffff0000, v45
	ds_bpermute_b32 v45, v26, v46
	ds_bpermute_b32 v23, v26, v22
	v_cvt_pk_bf16_f32 v47, v20, v21
	v_add_co_u32_e32 v20, vcc, 0xa002000, v18
	s_nop 1
	v_addc_co_u32_e32 v21, vcc, 0, v19, vcc
	global_store_dword v[20:21], v47, off offset:3200
	s_and_saveexec_b64 s[2:3], s[10:11]
	s_xor_b64 s[18:19], exec, s[2:3]
	s_cbranch_execz .LBB0_284
	s_waitcnt lgkmcnt(0)
	v_pk_mul_f32 v[22:23], v[222:223], v[22:23]
	v_mul_f32_e32 v20, v220, v46
	v_mul_f32_e32 v46, v221, v45
	v_mov_b32_e32 v21, v22
	v_mov_b32_e32 v47, v23
	v_pk_add_f32 v[20:21], v[20:21], v[46:47]
.LBB0_284:
	s_andn2_saveexec_b64 s[18:19], s[18:19]
	s_cbranch_execz .LBB0_286
	s_waitcnt lgkmcnt(0)
	v_pk_mul_f32 v[22:23], v[238:239], v[22:23]
	v_mul_f32_e32 v20, v236, v46
	v_mul_f32_e32 v46, v237, v45
	v_mov_b32_e32 v21, v22
	v_mov_b32_e32 v47, v23
	v_pk_add_f32 v[20:21], v[20:21], v[46:47] neg_lo:[0,1] neg_hi:[0,1]
; #define LAS __attribute__((address_space(3)))
; DI unsigned pk2(float lo, float hi) { f32x2 x = {lo, hi}; return __builtin_bit_cast(unsigned, __builtin_convertvector(x, bf16x2_t)); }
; DI float sum16(float v) { v += __shfl_xor(v, 8); v += __shfl_xor(v, 4); v += __shfl_xor(v, 2); v += __shfl_xor(v, 1); return v; }
; template <int HP> DI void rope2(f32x2& x, int hl, const LAS f32x2* cs) {
;   const float pa = __shfl_xor(x[0], HP), pb = __shfl_xor(x[1], HP);
;   if (hl < HP) { const f32x2 c0 = cs[2 * hl], c1 = cs[2 * hl + 1]; x[0] = x[0] * c0[0] - pa * c0[1]; x[1] = x[1] * c1[0] - pb * c1[1]; }
;   else if (hl < 2 * HP) { const f32x2 c0 = cs[2 * (hl - HP)], c1 = cs[2 * (hl - HP) + 1]; x[0] = x[0] * c0[0] + pa * c0[1]; x[1] = x[1] * c1[0] + pb * c1[1]; }
; DI void post_unit(const Params& p, int l, int unit, LAS unsigned char* lds) {
;     ...
;       } else if (s < 12) {
;         rope2<16>(x, hl, cs64 + t * 32);
;         const int hd = ((s & 1) ? 2 : 0) + hsel;
;         const float lg = log1pf(-exp2f(-5.0f - (float)hd));
;         const float f = (s < 10) ? expf(lg * (float)(t + 1)) : expf(lg * (float)(63 - t)) * 0.125f;
;         x *= f; *(unsigned*)pp = pk2(x[0], x[1]);
;       } else {
;         const float* gn = (s < 14) ? qnc : knc;
;         const float rs = rsqrtf(sum16(x[0] * x[0] + x[1] * x[1]) * (1.0f / 32.0f) + EPS);
;         x[0] *= rs * gn[2 * hl16]; x[1] *= rs * gn[2 * hl16 + 1]; rope2<2>(x, hl16, cs8 + t * 4);
;         if (s < 14) x *= LOG2E * 0.17677669529663687f;
;         *(unsigned*)pp = pk2(x[0], x[1]);
.LBB0_286:
	s_or_b64 exec, exec, s[18:19]
	s_waitcnt lgkmcnt(1)
	v_cvt_f32_i32_e32 v45, v38
	v_mul_f32_e32 v22, v31, v45
	s_waitcnt lgkmcnt(0)
	v_mul_f32_e32 v23, 0x3fb8aa3b, v22
	v_fma_f32 v46, v22, s64, -v23
	v_rndne_f32_e32 v47, v23
	v_fmac_f32_e32 v46, 0x32a5705f, v22
	v_sub_f32_e32 v23, v23, v47
	v_add_f32_e32 v23, v23, v46
	v_cvt_i32_f32_e32 v47, v47
	v_exp_f32_e32 v23, v23
	v_cmp_ngt_f32_e32 vcc, s65, v22
	s_waitcnt vmcnt(26)
	v_lshlrev_b32_e32 v46, 16, v44
	v_ldexp_f32 v23, v23, v47
	v_cndmask_b32_e32 v23, 0, v23, vcc
	v_cmp_nlt_f32_e32 vcc, s89, v22
	s_nop 1
	v_cndmask_b32_e32 v22, v177, v23, vcc
	v_mul_f32_e32 v22, 0x3e000000, v22
	v_pk_mul_f32 v[20:21], v[22:23], v[20:21] op_sel_hi:[0,1]
	v_and_b32_e32 v22, 0xffff0000, v44
	ds_bpermute_b32 v44, v26, v46
	ds_bpermute_b32 v23, v26, v22
	v_cvt_pk_bf16_f32 v47, v20, v21
	v_add_co_u32_e32 v20, vcc, 0xa002000, v18
	s_nop 1
	v_addc_co_u32_e32 v21, vcc, 0, v19, vcc
	global_store_dword v[20:21], v47, off offset:3456
	s_and_saveexec_b64 s[2:3], s[10:11]
	s_xor_b64 s[18:19], exec, s[2:3]
	s_cbranch_execz .LBB0_288
	s_waitcnt lgkmcnt(0)
	v_pk_mul_f32 v[22:23], v[222:223], v[22:23]
	v_mul_f32_e32 v20, v220, v46
	v_mul_f32_e32 v46, v221, v44
	v_mov_b32_e32 v21, v22
	v_mov_b32_e32 v47, v23
	v_pk_add_f32 v[20:21], v[20:21], v[46:47]
.LBB0_288:
	s_andn2_saveexec_b64 s[18:19], s[18:19]
	s_cbranch_execz .LBB0_290
	s_waitcnt lgkmcnt(0)
	v_pk_mul_f32 v[22:23], v[238:239], v[22:23]
	v_mul_f32_e32 v20, v236, v46
	v_mul_f32_e32 v46, v237, v44
	v_mov_b32_e32 v21, v22
	v_mov_b32_e32 v47, v23
	v_pk_add_f32 v[20:21], v[20:21], v[46:47] neg_lo:[0,1] neg_hi:[0,1]
.LBB0_290:
	s_or_b64 exec, exec, s[18:19]
	v_mul_f32_e32 v22, v32, v45
	s_waitcnt lgkmcnt(0)
	v_mul_f32_e32 v23, 0x3fb8aa3b, v22
	v_fma_f32 v44, v22, s64, -v23
	v_rndne_f32_e32 v45, v23
	v_fmac_f32_e32 v44, 0x32a5705f, v22
	v_sub_f32_e32 v23, v23, v45
	v_add_f32_e32 v23, v23, v44
	v_exp_f32_e32 v23, v23
	v_cvt_i32_f32_e32 v44, v45
	v_cmp_ngt_f32_e32 vcc, s65, v22
	v_ldexp_f32 v23, v23, v44
	s_nop 0
	v_cndmask_b32_e32 v23, 0, v23, vcc
	v_cmp_nlt_f32_e32 vcc, s89, v22
	s_nop 1
	v_cndmask_b32_e32 v22, v177, v23, vcc
	v_mul_f32_e32 v22, 0x3e000000, v22
	v_pk_mul_f32 v[20:21], v[22:23], v[20:21] op_sel_hi:[0,1]
	v_cvt_pk_bf16_f32 v22, v20, v21
	v_add_co_u32_e32 v20, vcc, s77, v18
	s_nop 1
	v_addc_co_u32_e32 v21, vcc, 0, v19, vcc
	global_store_dword v[20:21], v22, off offset:3712
	s_waitcnt vmcnt(27)
	v_lshlrev_b32_e32 v20, 16, v43
	v_and_b32_e32 v21, 0xffff0000, v43
	v_pk_mul_f32 v[22:23], v[20:21], v[20:21]
	s_nop 0
	v_add_f32_e32 v22, v22, v23
	s_nop 1
	v_add_f32_dpp v22, v22, v22 row_ror:8 row_mask:0xf bank_mask:0xf
	s_nop 1
	v_add_f32_dpp v22, v22, v22 row_ror:4 row_mask:0xf bank_mask:0xf
	s_nop 1
	v_add_f32_dpp v22, v22, v22 quad_perm:[2,3,0,1] row_mask:0xf bank_mask:0xf
	s_nop 1
	v_add_f32_dpp v22, v22, v22 quad_perm:[1,0,3,2] row_mask:0xf bank_mask:0xf
	v_fmamk_f32 v22, v22, 0x3d000000, v170
	v_cmp_gt_f32_e32 vcc, s33, v22
	v_mul_f32_e32 v23, 0x4b800000, v22
	s_nop 0
	v_cndmask_b32_e32 v22, v22, v23, vcc
	v_rsq_f32_e32 v22, v22
	s_nop 0
	v_mul_f32_e32 v23, 0x45800000, v22
	v_cndmask_b32_e32 v22, v22, v23, vcc
	v_pk_mul_f32 v[22:23], v[6:7], v[22:23] op_sel_hi:[1,0]
	s_nop 0
	v_pk_mul_f32 v[22:23], v[22:23], v[20:21]
	ds_bpermute_b32 v20, v29, v22
	ds_bpermute_b32 v21, v29, v23
	s_and_saveexec_b64 s[2:3], s[6:7]
	s_xor_b64 s[18:19], exec, s[2:3]
	s_cbranch_execz .LBB0_294
	s_and_saveexec_b64 s[30:31], s[8:9]
	s_cbranch_execz .LBB0_293
	s_waitcnt lgkmcnt(0)
	v_pk_mul_f32 v[48:49], v[22:23], v[228:229]
	v_mul_f32_e32 v22, v229, v20
	v_mov_b32_e32 v20, v23
	v_pk_mul_f32 v[20:21], v[20:21], v[230:231]
	s_nop 0
	v_mov_b32_e32 v49, v20
	v_mov_b32_e32 v23, v21
	v_pk_add_f32 v[22:23], v[48:49], v[22:23]

; #define LAS __attribute__((address_space(3)))
; DI unsigned pk2(float lo, float hi) { f32x2 x = {lo, hi}; return __builtin_bit_cast(unsigned, __builtin_convertvector(x, bf16x2_t)); }
; DI float sum16(float v) { v += __shfl_xor(v, 8); v += __shfl_xor(v, 4); v += __shfl_xor(v, 2); v += __shfl_xor(v, 1); return v; }
; template <int HP> DI void rope2(f32x2& x, int hl, const LAS f32x2* cs) {
;   const float pa = __shfl_xor(x[0], HP), pb = __shfl_xor(x[1], HP);
;   if (hl < HP) { const f32x2 c0 = cs[2 * hl], c1 = cs[2 * hl + 1]; x[0] = x[0] * c0[0] - pa * c0[1]; x[1] = x[1] * c1[0] - pb * c1[1]; }
;   else if (hl < 2 * HP) { const f32x2 c0 = cs[2 * (hl - HP)], c1 = cs[2 * (hl - HP) + 1]; x[0] = x[0] * c0[0] + pa * c0[1]; x[1] = x[1] * c1[0] + pb * c1[1]; }
; DI void post_unit(const Params& p, int l, int unit, LAS unsigned char* lds) {
;     ...
;       } else {
;         const float* gn = (s < 14) ? qnc : knc;
;         const float rs = rsqrtf(sum16(x[0] * x[0] + x[1] * x[1]) * (1.0f / 32.0f) + EPS);
;         x[0] *= rs * gn[2 * hl16]; x[1] *= rs * gn[2 * hl16 + 1]; rope2<2>(x, hl16, cs8 + t * 4);
;         if (s < 14) x *= LOG2E * 0.17677669529663687f;
;         *(unsigned*)pp = pk2(x[0], x[1]);
.LBB0_294:
	s_andn2_saveexec_b64 s[18:19], s[18:19]
	s_cbranch_execz .LBB0_296
	s_waitcnt lgkmcnt(0)
	v_pk_mul_f32 v[48:49], v[22:23], v[240:241]
	v_mul_f32_e32 v22, v241, v20
	v_mov_b32_e32 v20, v23
	v_pk_mul_f32 v[20:21], v[20:21], v[242:243]
	s_nop 0
	v_mov_b32_e32 v49, v20
	v_mov_b32_e32 v23, v21
	v_pk_add_f32 v[22:23], v[48:49], v[22:23] neg_lo:[0,1] neg_hi:[0,1]
.LBB0_296:
	s_or_b64 exec, exec, s[18:19]
	s_mov_b32 s2, 0x3e8293ee
	s_waitcnt lgkmcnt(0)
	v_pk_mul_f32 v[20:21], v[22:23], s[2:3] op_sel_hi:[1,0]
	s_nop 0
	v_cvt_pk_bf16_f32 v22, v20, v21
	v_add_co_u32_e32 v20, vcc, 0xa003000, v18
	s_nop 1
	v_addc_co_u32_e32 v21, vcc, 0, v19, vcc
	global_store_dword v[20:21], v22, off offset:896
	s_waitcnt vmcnt(27)
	v_lshlrev_b32_e32 v20, 16, v42
	v_and_b32_e32 v21, 0xffff0000, v42
	v_pk_mul_f32 v[22:23], v[20:21], v[20:21]
	s_nop 0
	v_add_f32_e32 v22, v22, v23
	s_nop 1
	v_add_f32_dpp v22, v22, v22 row_ror:8 row_mask:0xf bank_mask:0xf
	s_nop 1
	v_add_f32_dpp v22, v22, v22 row_ror:4 row_mask:0xf bank_mask:0xf
	s_nop 1
	v_add_f32_dpp v22, v22, v22 quad_perm:[2,3,0,1] row_mask:0xf bank_mask:0xf
	s_nop 1
	v_add_f32_dpp v22, v22, v22 quad_perm:[1,0,3,2] row_mask:0xf bank_mask:0xf
	v_fmamk_f32 v22, v22, 0x3d000000, v170
	v_cmp_gt_f32_e32 vcc, s33, v22
	v_mul_f32_e32 v23, 0x4b800000, v22
	s_nop 0
	v_cndmask_b32_e32 v22, v22, v23, vcc
	v_rsq_f32_e32 v22, v22
	s_nop 0
	v_mul_f32_e32 v23, 0x45800000, v22
	v_cndmask_b32_e32 v22, v22, v23, vcc
	v_pk_mul_f32 v[22:23], v[6:7], v[22:23] op_sel_hi:[1,0]
	s_nop 0
	v_pk_mul_f32 v[22:23], v[22:23], v[20:21]
	ds_bpermute_b32 v20, v29, v22
	ds_bpermute_b32 v21, v29, v23
	s_and_saveexec_b64 s[2:3], s[6:7]
	s_xor_b64 s[18:19], exec, s[2:3]
	s_cbranch_execz .LBB0_300
	s_and_saveexec_b64 s[30:31], s[8:9]
	s_cbranch_execz .LBB0_299
	s_waitcnt lgkmcnt(0)
	v_pk_mul_f32 v[46:47], v[22:23], v[228:229]
	v_mul_f32_e32 v22, v229, v20
	v_mov_b32_e32 v20, v23
	v_pk_mul_f32 v[20:21], v[20:21], v[230:231]
	s_nop 0
	v_mov_b32_e32 v47, v20
	v_mov_b32_e32 v23, v21
	v_pk_add_f32 v[22:23], v[46:47], v[22:23]

; #define LAS __attribute__((address_space(3)))
; DI unsigned pk2(float lo, float hi) { f32x2 x = {lo, hi}; return __builtin_bit_cast(unsigned, __builtin_convertvector(x, bf16x2_t)); }
; DI float sum16(float v) { v += __shfl_xor(v, 8); v += __shfl_xor(v, 4); v += __shfl_xor(v, 2); v += __shfl_xor(v, 1); return v; }
; template <int HP> DI void rope2(f32x2& x, int hl, const LAS f32x2* cs) {
;   const float pa = __shfl_xor(x[0], HP), pb = __shfl_xor(x[1], HP);
;   if (hl < HP) { const f32x2 c0 = cs[2 * hl], c1 = cs[2 * hl + 1]; x[0] = x[0] * c0[0] - pa * c0[1]; x[1] = x[1] * c1[0] - pb * c1[1]; }
;   else if (hl < 2 * HP) { const f32x2 c0 = cs[2 * (hl - HP)], c1 = cs[2 * (hl - HP) + 1]; x[0] = x[0] * c0[0] + pa * c0[1]; x[1] = x[1] * c1[0] + pb * c1[1]; }
; DI void post_unit(const Params& p, int l, int unit, LAS unsigned char* lds) {
;     ...
;       } else {
;         const float* gn = (s < 14) ? qnc : knc;
;         const float rs = rsqrtf(sum16(x[0] * x[0] + x[1] * x[1]) * (1.0f / 32.0f) + EPS);
;         x[0] *= rs * gn[2 * hl16]; x[1] *= rs * gn[2 * hl16 + 1]; rope2<2>(x, hl16, cs8 + t * 4);
;         if (s < 14) x *= LOG2E * 0.17677669529663687f;
;         *(unsigned*)pp = pk2(x[0], x[1]);
.LBB0_300:
	s_andn2_saveexec_b64 s[18:19], s[18:19]
	s_cbranch_execz .LBB0_302
	s_waitcnt lgkmcnt(0)
	v_pk_mul_f32 v[46:47], v[22:23], v[240:241]
	v_mul_f32_e32 v22, v241, v20
	v_mov_b32_e32 v20, v23
	v_pk_mul_f32 v[20:21], v[20:21], v[242:243]
	s_nop 0
	v_mov_b32_e32 v47, v20
	v_mov_b32_e32 v23, v21
	v_pk_add_f32 v[22:23], v[46:47], v[22:23] neg_lo:[0,1] neg_hi:[0,1]
.LBB0_302:
	s_or_b64 exec, exec, s[18:19]
	s_mov_b32 s2, 0x3e8293ee
	s_waitcnt lgkmcnt(0)
	v_pk_mul_f32 v[20:21], v[22:23], s[2:3] op_sel_hi:[1,0]
	s_nop 0
	v_cvt_pk_bf16_f32 v22, v20, v21
	v_add_co_u32_e32 v20, vcc, 0xa003000, v18
	s_nop 1
	v_addc_co_u32_e32 v21, vcc, 0, v19, vcc
	global_store_dword v[20:21], v22, off offset:1152
	s_waitcnt vmcnt(27)
	v_lshlrev_b32_e32 v20, 16, v41
	v_and_b32_e32 v21, 0xffff0000, v41
	v_pk_mul_f32 v[22:23], v[20:21], v[20:21]
	s_nop 0
	v_add_f32_e32 v22, v22, v23
	s_nop 1
	v_add_f32_dpp v22, v22, v22 row_ror:8 row_mask:0xf bank_mask:0xf
	s_nop 1
	v_add_f32_dpp v22, v22, v22 row_ror:4 row_mask:0xf bank_mask:0xf
	s_nop 1
	v_add_f32_dpp v22, v22, v22 quad_perm:[2,3,0,1] row_mask:0xf bank_mask:0xf
	s_nop 1
	v_add_f32_dpp v22, v22, v22 quad_perm:[1,0,3,2] row_mask:0xf bank_mask:0xf
	v_fmamk_f32 v22, v22, 0x3d000000, v170
	v_cmp_gt_f32_e32 vcc, s33, v22
	v_mul_f32_e32 v23, 0x4b800000, v22
	s_nop 0
	v_cndmask_b32_e32 v22, v22, v23, vcc
	v_rsq_f32_e32 v22, v22
	s_nop 0
	v_mul_f32_e32 v23, 0x45800000, v22
	v_cndmask_b32_e32 v22, v22, v23, vcc
	v_pk_mul_f32 v[22:23], v[8:9], v[22:23] op_sel_hi:[1,0]
	s_nop 0
	v_pk_mul_f32 v[22:23], v[22:23], v[20:21]
	ds_bpermute_b32 v20, v29, v22
	ds_bpermute_b32 v21, v29, v23
	s_and_saveexec_b64 s[2:3], s[6:7]
	s_xor_b64 s[18:19], exec, s[2:3]
	s_cbranch_execz .LBB0_306
	s_and_saveexec_b64 s[30:31], s[8:9]
	s_cbranch_execz .LBB0_305
	s_waitcnt lgkmcnt(0)
	v_pk_mul_f32 v[46:47], v[22:23], v[228:229]
	v_mul_f32_e32 v22, v229, v20
	v_mov_b32_e32 v20, v23
	v_pk_mul_f32 v[20:21], v[20:21], v[230:231]
	s_nop 0
	v_mov_b32_e32 v47, v20
	v_mov_b32_e32 v23, v21
	v_pk_add_f32 v[22:23], v[46:47], v[22:23]

; #define LAS __attribute__((address_space(3)))
; DI unsigned pk2(float lo, float hi) { f32x2 x = {lo, hi}; return __builtin_bit_cast(unsigned, __builtin_convertvector(x, bf16x2_t)); }
; DI float sum16(float v) { v += __shfl_xor(v, 8); v += __shfl_xor(v, 4); v += __shfl_xor(v, 2); v += __shfl_xor(v, 1); return v; }
; template <int HP> DI void rope2(f32x2& x, int hl, const LAS f32x2* cs) {
;   const float pa = __shfl_xor(x[0], HP), pb = __shfl_xor(x[1], HP);
;   if (hl < HP) { const f32x2 c0 = cs[2 * hl], c1 = cs[2 * hl + 1]; x[0] = x[0] * c0[0] - pa * c0[1]; x[1] = x[1] * c1[0] - pb * c1[1]; }
;   else if (hl < 2 * HP) { const f32x2 c0 = cs[2 * (hl - HP)], c1 = cs[2 * (hl - HP) + 1]; x[0] = x[0] * c0[0] + pa * c0[1]; x[1] = x[1] * c1[0] + pb * c1[1]; }
; DI void post_unit(const Params& p, int l, int unit, LAS unsigned char* lds) {
;     ...
;       } else {
;         const float* gn = (s < 14) ? qnc : knc;
;         const float rs = rsqrtf(sum16(x[0] * x[0] + x[1] * x[1]) * (1.0f / 32.0f) + EPS);
;         x[0] *= rs * gn[2 * hl16]; x[1] *= rs * gn[2 * hl16 + 1]; rope2<2>(x, hl16, cs8 + t * 4);
;         if (s < 14) x *= LOG2E * 0.17677669529663687f;
;         *(unsigned*)pp = pk2(x[0], x[1]);
.LBB0_308:
	s_or_b64 exec, exec, s[18:19]
	s_waitcnt lgkmcnt(1)
	v_add_co_u32_e32 v20, vcc, 0xa003000, v18
	v_cvt_pk_bf16_f32 v22, v22, v23
	s_waitcnt lgkmcnt(0)
	v_addc_co_u32_e32 v21, vcc, 0, v19, vcc
	global_store_dword v[20:21], v22, off offset:1408
	s_waitcnt vmcnt(27)
	v_lshlrev_b32_e32 v20, 16, v3
	v_and_b32_e32 v21, 0xffff0000, v3
	v_pk_mul_f32 v[22:23], v[20:21], v[20:21]
	s_nop 0
	v_add_f32_e32 v3, v22, v23
	s_nop 1
	v_add_f32_dpp v3, v3, v3 row_ror:8 row_mask:0xf bank_mask:0xf
	s_nop 1
	v_add_f32_dpp v3, v3, v3 row_ror:4 row_mask:0xf bank_mask:0xf
	s_nop 1
	v_add_f32_dpp v3, v3, v3 quad_perm:[2,3,0,1] row_mask:0xf bank_mask:0xf
	s_nop 1
	v_add_f32_dpp v3, v3, v3 quad_perm:[1,0,3,2] row_mask:0xf bank_mask:0xf
	v_fmamk_f32 v3, v3, 0x3d000000, v170
	v_cmp_gt_f32_e32 vcc, s33, v3
	v_mul_f32_e32 v22, 0x4b800000, v3
	s_nop 0
	v_cndmask_b32_e32 v3, v3, v22, vcc
	v_rsq_f32_e32 v3, v3
	s_nop 0
	v_mul_f32_e32 v22, 0x45800000, v3
	v_cndmask_b32_e32 v22, v3, v22, vcc
	v_pk_mul_f32 v[22:23], v[8:9], v[22:23] op_sel_hi:[1,0]
	s_nop 0
	v_pk_mul_f32 v[22:23], v[22:23], v[20:21]
	ds_bpermute_b32 v3, v29, v22
	ds_bpermute_b32 v21, v29, v23
	s_and_saveexec_b64 s[2:3], s[6:7]
	s_xor_b64 s[18:19], exec, s[2:3]
	s_cbranch_execz .LBB0_312
	s_and_saveexec_b64 s[30:31], s[8:9]
	s_cbranch_execz .LBB0_311
	v_mov_b32_e32 v20, v23
	s_waitcnt lgkmcnt(0)
	v_pk_mul_f32 v[46:47], v[22:23], v[228:229]
	v_pk_mul_f32 v[20:21], v[20:21], v[230:231]
	v_mul_f32_e32 v22, v229, v3
	v_mov_b32_e32 v47, v20
	v_mov_b32_e32 v23, v21
	v_pk_add_f32 v[22:23], v[46:47], v[22:23]

; #define LAS __attribute__((address_space(3)))
; template <int HP> DI void rope2(f32x2& x, int hl, const LAS f32x2* cs) {
;   const float pa = __shfl_xor(x[0], HP), pb = __shfl_xor(x[1], HP);
;   if (hl < HP) { const f32x2 c0 = cs[2 * hl], c1 = cs[2 * hl + 1]; x[0] = x[0] * c0[0] - pa * c0[1]; x[1] = x[1] * c1[0] - pb * c1[1]; }
;   else if (hl < 2 * HP) { const f32x2 c0 = cs[2 * (hl - HP)], c1 = cs[2 * (hl - HP) + 1]; x[0] = x[0] * c0[0] + pa * c0[1]; x[1] = x[1] * c1[0] + pb * c1[1]; }
; DI void post_unit(const Params& p, int l, int unit, LAS unsigned char* lds) {
;     ...
;   for (int tp = 0; tp < 4; ++tp) {
;     ...
;         x[0] *= rs * gn[2 * hl16]; x[1] *= rs * gn[2 * hl16 + 1]; rope2<2>(x, hl16, cs8 + t * 4);
.LBB0_312:
	s_andn2_saveexec_b64 s[18:19], s[18:19]
	s_cbranch_execz .LBB0_149
	v_mov_b32_e32 v20, v23
	s_waitcnt lgkmcnt(0)
	v_pk_mul_f32 v[46:47], v[22:23], v[240:241]
	v_pk_mul_f32 v[20:21], v[20:21], v[242:243]
	v_mul_f32_e32 v22, v241, v3
	v_mov_b32_e32 v47, v20
	v_mov_b32_e32 v23, v21
	v_pk_add_f32 v[22:23], v[46:47], v[22:23] neg_lo:[0,1] neg_hi:[0,1]
	s_branch .LBB0_149
